# first K-loop iteration peeled in the five whole-tile GEMM copies: first MFMA of each accumulator chain takes C=0, the per-unit accumulator zeroing (62 v_mov_b64) is gone; on top of v16
# speedup vs baseline: 1.0011x; 1.0011x over previous
.LBB0_132:
	s_ashr_i32 s25, s24, 31
	s_lshl_b64 s[28:29], s[24:25], 20
	v_readlane_b32 s25, v254, 62
	s_add_u32 s28, s25, s28
	v_readlane_b32 s25, v254, 63
	s_addc_u32 s29, s25, s29
	s_and_b64 s[4:5], s[4:5], exec
	s_cselect_b32 s25, s29, s31
	s_cselect_b32 s37, s28, s30
	s_add_u32 s50, s30, 0x100
	s_addc_u32 s51, s31, 0
	s_mov_b32 s57, -2
	s_add_u32 vcc_lo, s0, 0xffffc000
	s_addc_u32 vcc_hi, s1, -1
	s_mov_b32 m0, s52
	s_nop 0
	global_load_lds_dwordx4 v158, vcc
	s_mov_b32 m0, s53
	s_nop 0
	global_load_lds_dwordx4 v160, vcc
	ds_read_b128 v[130:133], v224
	ds_read_b128 v[134:137], v224 offset:1024
	ds_read_b128 v[138:141], v224 offset:2048
	ds_read_b128 v[142:145], v224 offset:3072
	ds_read_b128 v[146:149], v224 offset:16384
	ds_read_b128 v[162:165], v224 offset:17408
	ds_read_b128 v[166:169], v224 offset:18432
	ds_read_b128 v[170:173], v224 offset:19456
	ds_read_b128 v[174:177], v225
	ds_read_b128 v[178:181], v225 offset:1024
	ds_read_b128 v[182:185], v225 offset:2048
	ds_read_b128 v[186:189], v225 offset:3072
	ds_read_b128 v[190:193], v225 offset:4096
	ds_read_b128 v[204:207], v225 offset:5120
	ds_read_b128 v[208:211], v225 offset:6144
	ds_read_b128 v[212:215], v225 offset:7168
	s_add_u32 s4, s0, 0x100
	s_addc_u32 s5, s1, 0
	s_add_i32 s58, 0, 0x10000
	s_cmp_eq_u32 s57, 28
	s_cselect_b32 s35, s27, s5
	s_cselect_b32 s34, s26, s4
	s_cselect_b32 s31, s25, s51
	s_cselect_b32 s30, s37, s50
	s_add_i32 s59, 0, 0x14000
	s_add_i32 m0, s38, 0xc000
	s_nop 0
	global_load_lds_dwordx4 v158, s[0:1]
	s_add_i32 m0, s38, 0xe000
	s_nop 0
	global_load_lds_dwordx4 v160, s[0:1]
	s_waitcnt vmcnt(8)
	s_waitcnt lgkmcnt(0)
	v_mfma_f32_16x16x32_bf16 v[126:129], v[130:133], v[174:177], 0
	v_mfma_f32_16x16x32_bf16 v[126:129], v[134:137], v[178:181], v[126:129]
	s_barrier
	s_setprio 1
	v_mfma_f32_16x16x32_bf16 v[122:125], v[142:145], v[178:181], 0
	v_mfma_f32_16x16x32_bf16 v[122:125], v[138:141], v[174:177], v[122:125]
	v_mfma_f32_16x16x32_bf16 v[106:109], v[138:141], v[182:185], 0
	v_mfma_f32_16x16x32_bf16 v[106:109], v[142:145], v[186:189], v[106:109]
	v_mfma_f32_16x16x32_bf16 v[110:113], v[134:137], v[186:189], 0
	v_mfma_f32_16x16x32_bf16 v[110:113], v[130:133], v[182:185], v[110:113]
	v_mfma_f32_16x16x32_bf16 v[94:97], v[130:133], v[190:193], 0
	v_mfma_f32_16x16x32_bf16 v[94:97], v[134:137], v[204:207], v[94:97]
	v_mfma_f32_16x16x32_bf16 v[90:93], v[142:145], v[204:207], 0
	v_mfma_f32_16x16x32_bf16 v[90:93], v[138:141], v[190:193], v[90:93]
	v_mfma_f32_16x16x32_bf16 v[74:77], v[138:141], v[208:211], 0
	v_mfma_f32_16x16x32_bf16 v[74:77], v[142:145], v[212:215], v[74:77]
	v_mfma_f32_16x16x32_bf16 v[78:81], v[134:137], v[212:215], 0
	v_mfma_f32_16x16x32_bf16 v[78:81], v[130:133], v[208:211], v[78:81]
	v_mfma_f32_16x16x32_bf16 v[118:121], v[146:149], v[174:177], 0
	v_mfma_f32_16x16x32_bf16 v[118:121], v[162:165], v[178:181], v[118:121]
	v_mfma_f32_16x16x32_bf16 v[114:117], v[170:173], v[178:181], 0
	v_mfma_f32_16x16x32_bf16 v[114:117], v[166:169], v[174:177], v[114:117]
	v_mfma_f32_16x16x32_bf16 v[98:101], v[166:169], v[182:185], 0
	v_mfma_f32_16x16x32_bf16 v[98:101], v[170:173], v[186:189], v[98:101]
	v_mfma_f32_16x16x32_bf16 v[102:105], v[162:165], v[186:189], 0
	v_mfma_f32_16x16x32_bf16 v[102:105], v[146:149], v[182:185], v[102:105]
	v_mfma_f32_16x16x32_bf16 v[86:89], v[146:149], v[190:193], 0
	v_mfma_f32_16x16x32_bf16 v[86:89], v[162:165], v[204:207], v[86:89]
	v_mfma_f32_16x16x32_bf16 v[82:85], v[170:173], v[204:207], 0
	v_mfma_f32_16x16x32_bf16 v[82:85], v[166:169], v[190:193], v[82:85]
	v_mfma_f32_16x16x32_bf16 v[66:69], v[166:169], v[208:211], 0
	v_mfma_f32_16x16x32_bf16 v[66:69], v[170:173], v[212:215], v[66:69]
	v_mfma_f32_16x16x32_bf16 v[70:73], v[162:165], v[212:215], 0
	v_mfma_f32_16x16x32_bf16 v[70:73], v[146:149], v[208:211], v[70:73]
	s_setprio 0
	s_barrier
	ds_read_b128 v[174:177], v225 offset:16384
	ds_read_b128 v[178:181], v225 offset:17408
	ds_read_b128 v[182:185], v225 offset:18432
	ds_read_b128 v[186:189], v225 offset:19456
	ds_read_b128 v[190:193], v225 offset:20480
	ds_read_b128 v[204:207], v225 offset:21504
	ds_read_b128 v[208:211], v225 offset:22528
	ds_read_b128 v[212:215], v225 offset:23552
	s_add_i32 s0, s58, s15
	s_mov_b32 m0, s0
	s_nop 0
	global_load_lds_dwordx4 v152, s[30:31]
	s_add_i32 m0, s0, 0x2000
	s_add_u32 s0, s30, 0x80000
	s_addc_u32 s1, s31, 0
	s_add_i32 s58, s59, s15
	global_load_lds_dwordx4 v156, s[30:31]
	s_mov_b32 m0, s58
	s_nop 0
	global_load_lds_dwordx4 v152, s[0:1]
	s_add_i32 m0, s58, 0x2000
	s_nop 0
	global_load_lds_dwordx4 v156, s[0:1]
	s_waitcnt vmcnt(6)
	s_waitcnt lgkmcnt(0)
	v_mfma_f32_16x16x32_bf16 v[62:65], v[130:133], v[174:177], 0
	v_mfma_f32_16x16x32_bf16 v[62:65], v[134:137], v[178:181], v[62:65]
	s_barrier
	s_setprio 1
	v_mfma_f32_16x16x32_bf16 v[58:61], v[142:145], v[178:181], 0
	v_mfma_f32_16x16x32_bf16 v[58:61], v[138:141], v[174:177], v[58:61]
	v_mfma_f32_16x16x32_bf16 v[42:45], v[138:141], v[182:185], 0
	v_mfma_f32_16x16x32_bf16 v[42:45], v[142:145], v[186:189], v[42:45]
	v_mfma_f32_16x16x32_bf16 v[46:49], v[134:137], v[186:189], 0
	v_mfma_f32_16x16x32_bf16 v[46:49], v[130:133], v[182:185], v[46:49]
	v_mfma_f32_16x16x32_bf16 v[30:33], v[130:133], v[190:193], 0
	v_mfma_f32_16x16x32_bf16 v[30:33], v[134:137], v[204:207], v[30:33]
	v_mfma_f32_16x16x32_bf16 v[26:29], v[142:145], v[204:207], 0
	v_mfma_f32_16x16x32_bf16 v[26:29], v[138:141], v[190:193], v[26:29]
	v_mfma_f32_16x16x32_bf16 v[10:13], v[138:141], v[208:211], 0
	v_mfma_f32_16x16x32_bf16 v[10:13], v[142:145], v[212:215], v[10:13]
	v_mfma_f32_16x16x32_bf16 v[14:17], v[134:137], v[212:215], 0
	v_mfma_f32_16x16x32_bf16 v[14:17], v[130:133], v[208:211], v[14:17]
	v_mfma_f32_16x16x32_bf16 v[54:57], v[146:149], v[174:177], 0
	v_mfma_f32_16x16x32_bf16 v[54:57], v[162:165], v[178:181], v[54:57]
	v_mfma_f32_16x16x32_bf16 v[50:53], v[170:173], v[178:181], 0
	v_mfma_f32_16x16x32_bf16 v[50:53], v[166:169], v[174:177], v[50:53]
	v_mfma_f32_16x16x32_bf16 v[34:37], v[166:169], v[182:185], 0
	v_mfma_f32_16x16x32_bf16 v[34:37], v[170:173], v[186:189], v[34:37]
	v_mfma_f32_16x16x32_bf16 v[38:41], v[162:165], v[186:189], 0
	v_mfma_f32_16x16x32_bf16 v[38:41], v[146:149], v[182:185], v[38:41]
	v_mfma_f32_16x16x32_bf16 v[22:25], v[146:149], v[190:193], 0
	v_mfma_f32_16x16x32_bf16 v[22:25], v[162:165], v[204:207], v[22:25]
	v_mfma_f32_16x16x32_bf16 v[18:21], v[170:173], v[204:207], 0
	v_mfma_f32_16x16x32_bf16 v[18:21], v[166:169], v[190:193], v[18:21]
	v_mfma_f32_16x16x32_bf16 v[2:5], v[166:169], v[208:211], 0
	v_mfma_f32_16x16x32_bf16 v[2:5], v[170:173], v[212:215], v[2:5]
	v_mfma_f32_16x16x32_bf16 v[6:9], v[162:165], v[212:215], 0
	v_mfma_f32_16x16x32_bf16 v[6:9], v[146:149], v[208:211], v[6:9]
	s_setprio 0
	s_barrier
	s_mov_b32 m0, s38
	s_nop 0
	global_load_lds_dwordx4 v150, s[34:35]
	s_mov_b32 m0, s39
	s_nop 0
	global_load_lds_dwordx4 v154, s[34:35]
	ds_read_b128 v[130:133], v224 offset:32768
	ds_read_b128 v[134:137], v224 offset:33792
	ds_read_b128 v[138:141], v224 offset:34816
	ds_read_b128 v[142:145], v224 offset:35840
	ds_read_b128 v[146:149], v224 offset:49152
	ds_read_b128 v[162:165], v224 offset:50176
	ds_read_b128 v[166:169], v224 offset:51200
	ds_read_b128 v[170:173], v224 offset:52224
	ds_read_b128 v[174:177], v225 offset:32768
	ds_read_b128 v[178:181], v225 offset:33792
	ds_read_b128 v[182:185], v225 offset:34816
	ds_read_b128 v[186:189], v225 offset:35840
	ds_read_b128 v[190:193], v225 offset:36864
	ds_read_b128 v[204:207], v225 offset:37888
	ds_read_b128 v[208:211], v225 offset:38912
	ds_read_b128 v[212:215], v225 offset:39936
	s_add_i32 s58, 0, 0x18000
	s_add_i32 s59, 0, 0x1c000
	s_add_u32 s0, s34, 0x4000
	s_addc_u32 s1, s35, 0
	s_mov_b32 m0, s40
	s_nop 0
	global_load_lds_dwordx4 v150, s[0:1]
	s_mov_b32 m0, s41
	s_nop 0
	global_load_lds_dwordx4 v154, s[0:1]
	s_waitcnt vmcnt(8)
	s_waitcnt lgkmcnt(0)
	v_mfma_f32_16x16x32_bf16 v[126:129], v[130:133], v[174:177], v[126:129]
	v_mfma_f32_16x16x32_bf16 v[126:129], v[134:137], v[178:181], v[126:129]
	s_barrier
	s_setprio 1
	v_mfma_f32_16x16x32_bf16 v[122:125], v[142:145], v[178:181], v[122:125]
	v_mfma_f32_16x16x32_bf16 v[122:125], v[138:141], v[174:177], v[122:125]
	v_mfma_f32_16x16x32_bf16 v[106:109], v[138:141], v[182:185], v[106:109]
	v_mfma_f32_16x16x32_bf16 v[106:109], v[142:145], v[186:189], v[106:109]
	v_mfma_f32_16x16x32_bf16 v[110:113], v[134:137], v[186:189], v[110:113]
	v_mfma_f32_16x16x32_bf16 v[110:113], v[130:133], v[182:185], v[110:113]
	v_mfma_f32_16x16x32_bf16 v[94:97], v[130:133], v[190:193], v[94:97]
	v_mfma_f32_16x16x32_bf16 v[94:97], v[134:137], v[204:207], v[94:97]
	v_mfma_f32_16x16x32_bf16 v[90:93], v[142:145], v[204:207], v[90:93]
	v_mfma_f32_16x16x32_bf16 v[90:93], v[138:141], v[190:193], v[90:93]
	v_mfma_f32_16x16x32_bf16 v[74:77], v[138:141], v[208:211], v[74:77]
	v_mfma_f32_16x16x32_bf16 v[74:77], v[142:145], v[212:215], v[74:77]
	v_mfma_f32_16x16x32_bf16 v[78:81], v[134:137], v[212:215], v[78:81]
	v_mfma_f32_16x16x32_bf16 v[78:81], v[130:133], v[208:211], v[78:81]
	v_mfma_f32_16x16x32_bf16 v[118:121], v[146:149], v[174:177], v[118:121]
	v_mfma_f32_16x16x32_bf16 v[118:121], v[162:165], v[178:181], v[118:121]
	v_mfma_f32_16x16x32_bf16 v[114:117], v[170:173], v[178:181], v[114:117]
	v_mfma_f32_16x16x32_bf16 v[114:117], v[166:169], v[174:177], v[114:117]
	v_mfma_f32_16x16x32_bf16 v[98:101], v[166:169], v[182:185], v[98:101]
	v_mfma_f32_16x16x32_bf16 v[98:101], v[170:173], v[186:189], v[98:101]
	v_mfma_f32_16x16x32_bf16 v[102:105], v[162:165], v[186:189], v[102:105]
	v_mfma_f32_16x16x32_bf16 v[102:105], v[146:149], v[182:185], v[102:105]
	v_mfma_f32_16x16x32_bf16 v[86:89], v[146:149], v[190:193], v[86:89]
	v_mfma_f32_16x16x32_bf16 v[86:89], v[162:165], v[204:207], v[86:89]
	v_mfma_f32_16x16x32_bf16 v[82:85], v[170:173], v[204:207], v[82:85]
	v_mfma_f32_16x16x32_bf16 v[82:85], v[166:169], v[190:193], v[82:85]
	v_mfma_f32_16x16x32_bf16 v[66:69], v[166:169], v[208:211], v[66:69]
	v_mfma_f32_16x16x32_bf16 v[66:69], v[170:173], v[212:215], v[66:69]
	v_mfma_f32_16x16x32_bf16 v[70:73], v[162:165], v[212:215], v[70:73]
	v_mfma_f32_16x16x32_bf16 v[70:73], v[146:149], v[208:211], v[70:73]
	s_setprio 0
	s_barrier
	ds_read_b128 v[174:177], v225 offset:49152
	ds_read_b128 v[178:181], v225 offset:50176
	ds_read_b128 v[182:185], v225 offset:51200
	ds_read_b128 v[186:189], v225 offset:52224
	ds_read_b128 v[190:193], v225 offset:53248
	ds_read_b128 v[204:207], v225 offset:54272
	ds_read_b128 v[208:211], v225 offset:55296
	ds_read_b128 v[212:215], v225 offset:56320
	s_add_i32 s0, s58, s15
	s_add_u32 vcc_lo, s30, s94
	s_addc_u32 vcc_hi, s31, s95
	s_mov_b32 m0, s0
	s_nop 0
	global_load_lds_dwordx4 v152, vcc
	s_add_i32 m0, s0, 0x2000
	s_add_u32 s0, s30, 0x80080
	s_addc_u32 s1, s31, 0
	s_add_i32 s30, s59, s15
	global_load_lds_dwordx4 v156, vcc
	s_mov_b32 m0, s30
	s_nop 0
	global_load_lds_dwordx4 v152, s[0:1]
	s_add_i32 m0, s30, 0x2000
	s_nop 0
	global_load_lds_dwordx4 v156, s[0:1]
	s_waitcnt vmcnt(6)
	s_waitcnt lgkmcnt(0)
	v_mfma_f32_16x16x32_bf16 v[62:65], v[130:133], v[174:177], v[62:65]
	v_mfma_f32_16x16x32_bf16 v[62:65], v[134:137], v[178:181], v[62:65]
	s_barrier
	s_setprio 1
	v_mfma_f32_16x16x32_bf16 v[58:61], v[142:145], v[178:181], v[58:61]
	v_mfma_f32_16x16x32_bf16 v[58:61], v[138:141], v[174:177], v[58:61]
	v_mfma_f32_16x16x32_bf16 v[42:45], v[138:141], v[182:185], v[42:45]
	v_mfma_f32_16x16x32_bf16 v[42:45], v[142:145], v[186:189], v[42:45]
	v_mfma_f32_16x16x32_bf16 v[46:49], v[134:137], v[186:189], v[46:49]
	v_mfma_f32_16x16x32_bf16 v[46:49], v[130:133], v[182:185], v[46:49]
	v_mfma_f32_16x16x32_bf16 v[30:33], v[130:133], v[190:193], v[30:33]
	v_mfma_f32_16x16x32_bf16 v[30:33], v[134:137], v[204:207], v[30:33]
	v_mfma_f32_16x16x32_bf16 v[26:29], v[142:145], v[204:207], v[26:29]
	v_mfma_f32_16x16x32_bf16 v[26:29], v[138:141], v[190:193], v[26:29]
	v_mfma_f32_16x16x32_bf16 v[10:13], v[138:141], v[208:211], v[10:13]
	v_mfma_f32_16x16x32_bf16 v[10:13], v[142:145], v[212:215], v[10:13]
	s_add_i32 s57, s57, 2
	v_mfma_f32_16x16x32_bf16 v[14:17], v[134:137], v[212:215], v[14:17]
	v_mfma_f32_16x16x32_bf16 v[14:17], v[130:133], v[208:211], v[14:17]
	s_add_u32 s50, s50, 0x100
	v_mfma_f32_16x16x32_bf16 v[54:57], v[146:149], v[174:177], v[54:57]
	v_mfma_f32_16x16x32_bf16 v[54:57], v[162:165], v[178:181], v[54:57]
	s_addc_u32 s51, s51, 0
	v_mfma_f32_16x16x32_bf16 v[50:53], v[170:173], v[178:181], v[50:53]
	v_mfma_f32_16x16x32_bf16 v[50:53], v[166:169], v[174:177], v[50:53]
	s_cmp_gt_u32 s57, 29
	v_mfma_f32_16x16x32_bf16 v[34:37], v[166:169], v[182:185], v[34:37]
	v_mfma_f32_16x16x32_bf16 v[34:37], v[170:173], v[186:189], v[34:37]
	s_mov_b64 s[0:1], s[4:5]
	v_mfma_f32_16x16x32_bf16 v[38:41], v[162:165], v[186:189], v[38:41]
	v_mfma_f32_16x16x32_bf16 v[38:41], v[146:149], v[182:185], v[38:41]
	v_mfma_f32_16x16x32_bf16 v[22:25], v[146:149], v[190:193], v[22:25]
	v_mfma_f32_16x16x32_bf16 v[22:25], v[162:165], v[204:207], v[22:25]
	v_mfma_f32_16x16x32_bf16 v[18:21], v[170:173], v[204:207], v[18:21]
	v_mfma_f32_16x16x32_bf16 v[18:21], v[166:169], v[190:193], v[18:21]
	v_mfma_f32_16x16x32_bf16 v[2:5], v[166:169], v[208:211], v[2:5]
	v_mfma_f32_16x16x32_bf16 v[2:5], v[170:173], v[212:215], v[2:5]
	v_mfma_f32_16x16x32_bf16 v[6:9], v[162:165], v[212:215], v[6:9]
	v_mfma_f32_16x16x32_bf16 v[6:9], v[146:149], v[208:211], v[6:9]
	s_setprio 0
	s_barrier
	s_cbranch_scc1 .Lpeel_exit_0

.Lpeel_exit_0:
.LBB0_136:
	s_and_b64 vcc, exec, s[2:3]
	s_and_b32 s50, s33, 1
	s_cbranch_vccnz .LBB0_141
	v_mov_b32_e32 v131, v0
	s_mov_b32 s25, s24
	v_readfirstlane_b32 s4, v131
	s_ashr_i32 s1, s4, 8
	s_bfe_u32 s5, s4, 0x20006
	s_mov_b32 s4, s56
	s_xor_b32 s0, s50, 1
	s_add_i32 s30, s25, -16
	s_cmp_gt_u32 s30, 23
	v_and_b32_e32 v130, 63, v131
	s_cbranch_scc1 .LBB0_139
	s_lshl_b32 s25, s25, 8
	v_lshlrev_b32_e32 v132, 2, v130
	s_addk_i32 s25, 0xf000
	v_and_b32_e32 v132, 0x80, v132
	v_and_b32_e32 v131, 31, v131
	v_or_b32_e32 v132, s25, v132
	s_lshl_b32 s25, s5, 5
	s_lshl_b32 s30, s1, 2
	v_or3_b32 v194, v132, s25, v131
	s_mul_i32 s25, s0, 0x3000
	s_or_b32 s30, s30, s5
	s_add_i32 s25, s25, 0
	s_mulk_i32 s30, 0x600
	s_add_i32 s25, s25, s30
	v_lshlrev_b64 v[132:133], 2, v[194:195]
	s_add_i32 m0, s25, 0x20000
	v_lshl_add_u64 v[134:135], s[6:7], 0, v[132:133]
	global_load_lds_dword v[134:135], off
	v_lshl_add_u64 v[134:135], s[18:19], 0, v[132:133]
	s_add_i32 m0, s25, 0x20100
	s_nop 0
	global_load_lds_dword v[134:135], off
	v_lshl_add_u64 v[134:135], s[20:21], 0, v[132:133]
	s_add_i32 m0, s25, 0x20200
	s_nop 0
	global_load_lds_dword v[134:135], off
	v_lshl_add_u64 v[134:135], s[22:23], 0, v[132:133]
	s_add_i32 m0, s25, 0x20300
	v_lshl_add_u64 v[132:133], s[8:9], 0, v[132:133]
	global_load_lds_dword v[134:135], off
	s_add_i32 m0, s25, 0x20400
	s_nop 0
	global_load_lds_dword v[132:133], off

.LBB0_529:
	s_lshl_b32 s10, s30, 8
	s_ashr_i32 s11, s10, 31
	s_lshl_b64 s[10:11], s[10:11], 12
	s_add_u32 s10, s86, s10
	s_addc_u32 s11, s87, s11
	s_and_b64 s[12:13], s[2:3], exec
	s_cselect_b32 s34, s11, s15
	s_cselect_b32 s35, s10, s14
	s_ashr_i32 s9, s8, 31
	s_lshl_b64 s[12:13], s[8:9], 20
	v_readlane_b32 s9, v254, 62
	s_add_u32 s12, s9, s12
	v_readlane_b32 s9, v254, 63
	s_addc_u32 s13, s9, s13
	s_and_b64 s[18:19], s[2:3], exec
	s_cselect_b32 s9, s13, s17
	s_cselect_b32 s36, s12, s16
	s_add_u32 s14, s14, 0x80080
	s_addc_u32 s15, s15, 0
	s_add_u32 s37, s16, 0x100
	s_addc_u32 s38, s17, 0
	s_mov_b32 s39, -2
	s_add_u32 vcc_lo, s14, 0xfff80000
	s_addc_u32 vcc_hi, s15, -1
	s_mov_b32 m0, s27
	s_nop 0
	global_load_lds_dwordx4 v138, vcc
	s_mov_b32 m0, s28
	s_nop 0
	global_load_lds_dwordx4 v140, vcc
	ds_read_b128 v[152:155], v145
	ds_read_b128 v[156:159], v145 offset:1024
	ds_read_b128 v[160:163], v145 offset:2048
	ds_read_b128 v[164:167], v145 offset:3072
	ds_read_b128 v[168:171], v145 offset:16384
	ds_read_b128 v[172:175], v145 offset:17408
	ds_read_b128 v[176:179], v145 offset:18432
	ds_read_b128 v[180:183], v145 offset:19456
	ds_read_b128 v[184:187], v151
	ds_read_b128 v[188:191], v151 offset:1024
	ds_read_b128 v[204:207], v151 offset:2048
	ds_read_b128 v[208:211], v151 offset:3072
	ds_read_b128 v[212:215], v151 offset:4096
	ds_read_b128 v[216:219], v151 offset:5120
	ds_read_b128 v[220:223], v151 offset:6144
	ds_read_b128 v[224:227], v151 offset:7168
	s_add_u32 s16, s14, 0xfff80080
	s_addc_u32 s17, s15, -1
	s_add_i32 s40, 0, 0x10000
	s_cmp_eq_u32 s39, 28
	s_cselect_b32 s19, s34, s17
	s_cselect_b32 s18, s35, s16
	s_cselect_b32 s17, s9, s38
	s_cselect_b32 s16, s36, s37
	s_add_i32 s42, 0, 0x14000
	s_add_i32 m0, s23, 0xc000
	s_nop 0
	global_load_lds_dwordx4 v138, s[14:15]
	s_add_i32 m0, s23, 0xe000
	s_nop 0
	global_load_lds_dwordx4 v140, s[14:15]
	s_waitcnt vmcnt(8)
	s_waitcnt lgkmcnt(0)
	v_mfma_f32_16x16x32_bf16 v[126:129], v[152:155], v[184:187], 0
	v_mfma_f32_16x16x32_bf16 v[126:129], v[156:159], v[188:191], v[126:129]
	s_barrier
	s_setprio 1
	v_mfma_f32_16x16x32_bf16 v[122:125], v[164:167], v[188:191], 0
	v_mfma_f32_16x16x32_bf16 v[122:125], v[160:163], v[184:187], v[122:125]
	v_mfma_f32_16x16x32_bf16 v[106:109], v[160:163], v[204:207], 0
	v_mfma_f32_16x16x32_bf16 v[106:109], v[164:167], v[208:211], v[106:109]
	v_mfma_f32_16x16x32_bf16 v[110:113], v[156:159], v[208:211], 0
	v_mfma_f32_16x16x32_bf16 v[110:113], v[152:155], v[204:207], v[110:113]
	v_mfma_f32_16x16x32_bf16 v[94:97], v[152:155], v[212:215], 0
	v_mfma_f32_16x16x32_bf16 v[94:97], v[156:159], v[216:219], v[94:97]
	v_mfma_f32_16x16x32_bf16 v[90:93], v[164:167], v[216:219], 0
	v_mfma_f32_16x16x32_bf16 v[90:93], v[160:163], v[212:215], v[90:93]
	v_mfma_f32_16x16x32_bf16 v[74:77], v[160:163], v[220:223], 0
	v_mfma_f32_16x16x32_bf16 v[74:77], v[164:167], v[224:227], v[74:77]
	v_mfma_f32_16x16x32_bf16 v[78:81], v[156:159], v[224:227], 0
	v_mfma_f32_16x16x32_bf16 v[78:81], v[152:155], v[220:223], v[78:81]
	v_mfma_f32_16x16x32_bf16 v[118:121], v[168:171], v[184:187], 0
	v_mfma_f32_16x16x32_bf16 v[118:121], v[172:175], v[188:191], v[118:121]
	v_mfma_f32_16x16x32_bf16 v[114:117], v[180:183], v[188:191], 0
	v_mfma_f32_16x16x32_bf16 v[114:117], v[176:179], v[184:187], v[114:117]
	v_mfma_f32_16x16x32_bf16 v[98:101], v[176:179], v[204:207], 0
	v_mfma_f32_16x16x32_bf16 v[98:101], v[180:183], v[208:211], v[98:101]
	v_mfma_f32_16x16x32_bf16 v[102:105], v[172:175], v[208:211], 0
	v_mfma_f32_16x16x32_bf16 v[102:105], v[168:171], v[204:207], v[102:105]
	v_mfma_f32_16x16x32_bf16 v[86:89], v[168:171], v[212:215], 0
	v_mfma_f32_16x16x32_bf16 v[86:89], v[172:175], v[216:219], v[86:89]
	v_mfma_f32_16x16x32_bf16 v[82:85], v[180:183], v[216:219], 0
	v_mfma_f32_16x16x32_bf16 v[82:85], v[176:179], v[212:215], v[82:85]
	v_mfma_f32_16x16x32_bf16 v[66:69], v[176:179], v[220:223], 0
	v_mfma_f32_16x16x32_bf16 v[66:69], v[180:183], v[224:227], v[66:69]
	v_mfma_f32_16x16x32_bf16 v[70:73], v[172:175], v[224:227], 0
	v_mfma_f32_16x16x32_bf16 v[70:73], v[168:171], v[220:223], v[70:73]
	s_setprio 0
	s_barrier
	ds_read_b128 v[184:187], v151 offset:16384
	ds_read_b128 v[188:191], v151 offset:17408
	ds_read_b128 v[204:207], v151 offset:18432
	ds_read_b128 v[208:211], v151 offset:19456
	ds_read_b128 v[212:215], v151 offset:20480
	ds_read_b128 v[216:219], v151 offset:21504
	ds_read_b128 v[220:223], v151 offset:22528
	ds_read_b128 v[224:227], v151 offset:23552
	s_add_i32 s40, s40, s22
	s_mov_b32 m0, s40
	s_nop 0
	global_load_lds_dwordx4 v134, s[16:17]
	s_add_i32 m0, s40, 0x2000
	s_add_u32 s40, s16, 0x80000
	s_addc_u32 s41, s17, 0
	s_add_i32 s42, s42, s22
	global_load_lds_dwordx4 v130, s[16:17]
	s_mov_b32 m0, s42
	s_nop 0
	global_load_lds_dwordx4 v134, s[40:41]
	s_add_i32 m0, s42, 0x2000
	s_nop 0
	global_load_lds_dwordx4 v130, s[40:41]
	s_waitcnt vmcnt(6)
	s_waitcnt lgkmcnt(0)
	v_mfma_f32_16x16x32_bf16 v[62:65], v[152:155], v[184:187], 0
	v_mfma_f32_16x16x32_bf16 v[62:65], v[156:159], v[188:191], v[62:65]
	s_barrier
	s_setprio 1
	v_mfma_f32_16x16x32_bf16 v[58:61], v[164:167], v[188:191], 0
	v_mfma_f32_16x16x32_bf16 v[58:61], v[160:163], v[184:187], v[58:61]
	v_mfma_f32_16x16x32_bf16 v[42:45], v[160:163], v[204:207], 0
	v_mfma_f32_16x16x32_bf16 v[42:45], v[164:167], v[208:211], v[42:45]
	v_mfma_f32_16x16x32_bf16 v[46:49], v[156:159], v[208:211], 0
	v_mfma_f32_16x16x32_bf16 v[46:49], v[152:155], v[204:207], v[46:49]
	v_mfma_f32_16x16x32_bf16 v[30:33], v[152:155], v[212:215], 0
	v_mfma_f32_16x16x32_bf16 v[30:33], v[156:159], v[216:219], v[30:33]
	v_mfma_f32_16x16x32_bf16 v[26:29], v[164:167], v[216:219], 0
	v_mfma_f32_16x16x32_bf16 v[26:29], v[160:163], v[212:215], v[26:29]
	v_mfma_f32_16x16x32_bf16 v[10:13], v[160:163], v[220:223], 0
	v_mfma_f32_16x16x32_bf16 v[10:13], v[164:167], v[224:227], v[10:13]
	v_mfma_f32_16x16x32_bf16 v[14:17], v[156:159], v[224:227], 0
	v_mfma_f32_16x16x32_bf16 v[14:17], v[152:155], v[220:223], v[14:17]
	v_mfma_f32_16x16x32_bf16 v[54:57], v[168:171], v[184:187], 0
	v_mfma_f32_16x16x32_bf16 v[54:57], v[172:175], v[188:191], v[54:57]
	v_mfma_f32_16x16x32_bf16 v[50:53], v[180:183], v[188:191], 0
	v_mfma_f32_16x16x32_bf16 v[50:53], v[176:179], v[184:187], v[50:53]
	v_mfma_f32_16x16x32_bf16 v[34:37], v[176:179], v[204:207], 0
	v_mfma_f32_16x16x32_bf16 v[34:37], v[180:183], v[208:211], v[34:37]
	v_mfma_f32_16x16x32_bf16 v[38:41], v[172:175], v[208:211], 0
	v_mfma_f32_16x16x32_bf16 v[38:41], v[168:171], v[204:207], v[38:41]
	v_mfma_f32_16x16x32_bf16 v[22:25], v[168:171], v[212:215], 0
	v_mfma_f32_16x16x32_bf16 v[22:25], v[172:175], v[216:219], v[22:25]
	v_mfma_f32_16x16x32_bf16 v[18:21], v[180:183], v[216:219], 0
	v_mfma_f32_16x16x32_bf16 v[18:21], v[176:179], v[212:215], v[18:21]
	v_mfma_f32_16x16x32_bf16 v[2:5], v[176:179], v[220:223], 0
	v_mfma_f32_16x16x32_bf16 v[2:5], v[180:183], v[224:227], v[2:5]
	v_mfma_f32_16x16x32_bf16 v[6:9], v[172:175], v[224:227], 0
	v_mfma_f32_16x16x32_bf16 v[6:9], v[168:171], v[220:223], v[6:9]
	s_setprio 0
	s_barrier
	s_mov_b32 m0, s23
	s_nop 0
	global_load_lds_dwordx4 v136, s[18:19]
	s_mov_b32 m0, s24
	s_nop 0
	global_load_lds_dwordx4 v132, s[18:19]
	ds_read_b128 v[152:155], v145 offset:32768
	ds_read_b128 v[156:159], v145 offset:33792
	ds_read_b128 v[160:163], v145 offset:34816
	ds_read_b128 v[164:167], v145 offset:35840
	ds_read_b128 v[168:171], v145 offset:49152
	ds_read_b128 v[172:175], v145 offset:50176
	ds_read_b128 v[176:179], v145 offset:51200
	ds_read_b128 v[180:183], v145 offset:52224
	ds_read_b128 v[184:187], v151 offset:32768
	ds_read_b128 v[188:191], v151 offset:33792
	ds_read_b128 v[204:207], v151 offset:34816
	ds_read_b128 v[208:211], v151 offset:35840
	ds_read_b128 v[212:215], v151 offset:36864
	ds_read_b128 v[216:219], v151 offset:37888
	ds_read_b128 v[220:223], v151 offset:38912
	ds_read_b128 v[224:227], v151 offset:39936
	s_add_i32 s40, 0, 0x18000
	s_add_i32 s41, 0, 0x1c000
	s_add_u32 s18, s18, 0x80000
	s_addc_u32 s19, s19, 0
	s_mov_b32 m0, s25
	s_nop 0
	global_load_lds_dwordx4 v136, s[18:19]
	s_mov_b32 m0, s26
	s_nop 0
	global_load_lds_dwordx4 v132, s[18:19]
	s_waitcnt vmcnt(8)
	s_waitcnt lgkmcnt(0)
	v_mfma_f32_16x16x32_bf16 v[126:129], v[152:155], v[184:187], v[126:129]
	v_mfma_f32_16x16x32_bf16 v[126:129], v[156:159], v[188:191], v[126:129]
	s_barrier
	s_setprio 1
	v_mfma_f32_16x16x32_bf16 v[122:125], v[164:167], v[188:191], v[122:125]
	v_mfma_f32_16x16x32_bf16 v[122:125], v[160:163], v[184:187], v[122:125]
	v_mfma_f32_16x16x32_bf16 v[106:109], v[160:163], v[204:207], v[106:109]
	v_mfma_f32_16x16x32_bf16 v[106:109], v[164:167], v[208:211], v[106:109]
	v_mfma_f32_16x16x32_bf16 v[110:113], v[156:159], v[208:211], v[110:113]
	v_mfma_f32_16x16x32_bf16 v[110:113], v[152:155], v[204:207], v[110:113]
	v_mfma_f32_16x16x32_bf16 v[94:97], v[152:155], v[212:215], v[94:97]
	v_mfma_f32_16x16x32_bf16 v[94:97], v[156:159], v[216:219], v[94:97]
	v_mfma_f32_16x16x32_bf16 v[90:93], v[164:167], v[216:219], v[90:93]
	v_mfma_f32_16x16x32_bf16 v[90:93], v[160:163], v[212:215], v[90:93]
	v_mfma_f32_16x16x32_bf16 v[74:77], v[160:163], v[220:223], v[74:77]
	v_mfma_f32_16x16x32_bf16 v[74:77], v[164:167], v[224:227], v[74:77]
	v_mfma_f32_16x16x32_bf16 v[78:81], v[156:159], v[224:227], v[78:81]
	v_mfma_f32_16x16x32_bf16 v[78:81], v[152:155], v[220:223], v[78:81]
	v_mfma_f32_16x16x32_bf16 v[118:121], v[168:171], v[184:187], v[118:121]
	v_mfma_f32_16x16x32_bf16 v[118:121], v[172:175], v[188:191], v[118:121]
	v_mfma_f32_16x16x32_bf16 v[114:117], v[180:183], v[188:191], v[114:117]
	v_mfma_f32_16x16x32_bf16 v[114:117], v[176:179], v[184:187], v[114:117]
	v_mfma_f32_16x16x32_bf16 v[98:101], v[176:179], v[204:207], v[98:101]
	v_mfma_f32_16x16x32_bf16 v[98:101], v[180:183], v[208:211], v[98:101]
	v_mfma_f32_16x16x32_bf16 v[102:105], v[172:175], v[208:211], v[102:105]
	v_mfma_f32_16x16x32_bf16 v[102:105], v[168:171], v[204:207], v[102:105]
	v_mfma_f32_16x16x32_bf16 v[86:89], v[168:171], v[212:215], v[86:89]
	v_mfma_f32_16x16x32_bf16 v[86:89], v[172:175], v[216:219], v[86:89]
	v_mfma_f32_16x16x32_bf16 v[82:85], v[180:183], v[216:219], v[82:85]
	v_mfma_f32_16x16x32_bf16 v[82:85], v[176:179], v[212:215], v[82:85]
	v_mfma_f32_16x16x32_bf16 v[66:69], v[176:179], v[220:223], v[66:69]
	v_mfma_f32_16x16x32_bf16 v[66:69], v[180:183], v[224:227], v[66:69]
	v_mfma_f32_16x16x32_bf16 v[70:73], v[172:175], v[224:227], v[70:73]
	v_mfma_f32_16x16x32_bf16 v[70:73], v[168:171], v[220:223], v[70:73]
	s_setprio 0
	s_barrier
	ds_read_b128 v[184:187], v151 offset:49152
	ds_read_b128 v[188:191], v151 offset:50176
	ds_read_b128 v[204:207], v151 offset:51200
	ds_read_b128 v[208:211], v151 offset:52224
	ds_read_b128 v[212:215], v151 offset:53248
	ds_read_b128 v[216:219], v151 offset:54272
	ds_read_b128 v[220:223], v151 offset:55296
	ds_read_b128 v[224:227], v151 offset:56320
	s_add_i32 s18, s40, s22
	s_add_u32 vcc_lo, s16, s94
	s_addc_u32 vcc_hi, s17, s95
	s_mov_b32 m0, s18
	s_nop 0
	global_load_lds_dwordx4 v134, vcc
	s_add_i32 m0, s18, 0x2000
	s_add_u32 s16, s16, 0x80080
	s_addc_u32 s17, s17, 0
	s_add_i32 s18, s41, s22
	global_load_lds_dwordx4 v130, vcc
	s_mov_b32 m0, s18
	s_nop 0
	global_load_lds_dwordx4 v134, s[16:17]
	s_add_i32 m0, s18, 0x2000
	s_nop 0
	global_load_lds_dwordx4 v130, s[16:17]
	s_waitcnt vmcnt(6)
	s_waitcnt lgkmcnt(0)
	v_mfma_f32_16x16x32_bf16 v[62:65], v[152:155], v[184:187], v[62:65]
	v_mfma_f32_16x16x32_bf16 v[62:65], v[156:159], v[188:191], v[62:65]
	s_barrier
	s_setprio 1
	v_mfma_f32_16x16x32_bf16 v[58:61], v[164:167], v[188:191], v[58:61]
	v_mfma_f32_16x16x32_bf16 v[58:61], v[160:163], v[184:187], v[58:61]
	v_mfma_f32_16x16x32_bf16 v[42:45], v[160:163], v[204:207], v[42:45]
	v_mfma_f32_16x16x32_bf16 v[42:45], v[164:167], v[208:211], v[42:45]
	v_mfma_f32_16x16x32_bf16 v[46:49], v[156:159], v[208:211], v[46:49]
	v_mfma_f32_16x16x32_bf16 v[46:49], v[152:155], v[204:207], v[46:49]
	v_mfma_f32_16x16x32_bf16 v[30:33], v[152:155], v[212:215], v[30:33]
	v_mfma_f32_16x16x32_bf16 v[30:33], v[156:159], v[216:219], v[30:33]
	v_mfma_f32_16x16x32_bf16 v[26:29], v[164:167], v[216:219], v[26:29]
	v_mfma_f32_16x16x32_bf16 v[26:29], v[160:163], v[212:215], v[26:29]
	v_mfma_f32_16x16x32_bf16 v[10:13], v[160:163], v[220:223], v[10:13]
	v_mfma_f32_16x16x32_bf16 v[10:13], v[164:167], v[224:227], v[10:13]
	s_add_i32 s39, s39, 2
	v_mfma_f32_16x16x32_bf16 v[14:17], v[156:159], v[224:227], v[14:17]
	v_mfma_f32_16x16x32_bf16 v[14:17], v[152:155], v[220:223], v[14:17]
	s_add_u32 s14, s14, 0x100
	v_mfma_f32_16x16x32_bf16 v[54:57], v[168:171], v[184:187], v[54:57]
	v_mfma_f32_16x16x32_bf16 v[54:57], v[172:175], v[188:191], v[54:57]
	s_addc_u32 s15, s15, 0
	v_mfma_f32_16x16x32_bf16 v[50:53], v[180:183], v[188:191], v[50:53]
	v_mfma_f32_16x16x32_bf16 v[50:53], v[176:179], v[184:187], v[50:53]
	s_add_u32 s37, s37, 0x100
	v_mfma_f32_16x16x32_bf16 v[34:37], v[176:179], v[204:207], v[34:37]
	v_mfma_f32_16x16x32_bf16 v[34:37], v[180:183], v[208:211], v[34:37]
	s_addc_u32 s38, s38, 0
	v_mfma_f32_16x16x32_bf16 v[38:41], v[172:175], v[208:211], v[38:41]
	v_mfma_f32_16x16x32_bf16 v[38:41], v[168:171], v[204:207], v[38:41]
	s_cmp_gt_u32 s39, 29
	v_mfma_f32_16x16x32_bf16 v[22:25], v[168:171], v[212:215], v[22:25]
	v_mfma_f32_16x16x32_bf16 v[22:25], v[172:175], v[216:219], v[22:25]
	v_mfma_f32_16x16x32_bf16 v[18:21], v[180:183], v[216:219], v[18:21]
	v_mfma_f32_16x16x32_bf16 v[18:21], v[176:179], v[212:215], v[18:21]
	v_mfma_f32_16x16x32_bf16 v[2:5], v[176:179], v[220:223], v[2:5]
	v_mfma_f32_16x16x32_bf16 v[2:5], v[180:183], v[224:227], v[2:5]
	v_mfma_f32_16x16x32_bf16 v[6:9], v[172:175], v[224:227], v[6:9]
	v_mfma_f32_16x16x32_bf16 v[6:9], v[168:171], v[220:223], v[6:9]
	s_setprio 0
	s_barrier
	s_cbranch_scc1 .Lpeel_exit_2

.Lpeel_exit_2:
.LBB0_533:
	v_lshl_add_u32 v158, s33, 8, v143
	v_ashrrev_i32_e32 v159, 31, v158
	v_lshl_add_u64 v[152:153], v[158:159], 3, s[4:5]
	global_load_dwordx2 v[154:155], v[152:153], off
	global_load_dwordx2 v[162:163], v[152:153], off offset:128
	global_load_dwordx2 v[164:165], v[152:153], off offset:256
	global_load_dwordx2 v[166:167], v[152:153], off offset:384
	global_load_dwordx2 v[168:169], v[152:153], off offset:1024
	global_load_dwordx2 v[170:171], v[152:153], off offset:1152
	global_load_dwordx2 v[172:173], v[152:153], off offset:1280
	global_load_dwordx2 v[174:175], v[152:153], off offset:1408
	s_and_b64 vcc, exec, s[6:7]
	s_cbranch_vccz .Lalign_l2
	s_barrier

.LBB0_849:
	s_add_u32 s18, s18, 0x80
	s_addc_u32 s19, s19, 0
	s_add_u32 s51, s20, 0x100
	s_waitcnt lgkmcnt(0)
	s_waitcnt vmcnt(0)
	s_addc_u32 s54, s21, 0
	s_mov_b32 s20, 0
	s_sub_u32 vcc_lo, s18, s12
	s_subb_u32 vcc_hi, s19, 0
	s_mov_b32 m0, s33
	s_nop 0
	global_load_lds_dwordx4 v210, vcc
	s_mov_b32 m0, s34
	s_nop 0
	global_load_lds_dwordx4 v212, vcc
	ds_read_b128 v[66:69], v198
	ds_read_b128 v[78:81], v198 offset:1024
	ds_read_b128 v[82:85], v198 offset:2048
	ds_read_b128 v[98:101], v198 offset:3072
	ds_read_b128 v[106:109], v198 offset:16384
	ds_read_b128 v[118:121], v198 offset:17408
	ds_read_b128 v[130:133], v198 offset:18432
	ds_read_b128 v[142:145], v198 offset:19456
	ds_read_b128 v[150:153], v234
	ds_read_b128 v[154:157], v234 offset:1024
	ds_read_b128 v[158:161], v234 offset:2048
	ds_read_b128 v[162:165], v234 offset:3072
	ds_read_b128 v[170:173], v234 offset:4096
	ds_read_b128 v[174:177], v234 offset:5120
	ds_read_b128 v[178:181], v234 offset:6144
	ds_read_b128 v[190:193], v234 offset:7168
	s_add_i32 s55, s20, 2
	s_add_u32 s56, s18, 0x80
	s_addc_u32 s21, s19, 0
	s_add_i32 s58, 0, 0x10000
	s_cmp_eq_u32 s35, s20
	s_cselect_b32 s21, s1, s21
	s_cselect_b32 s20, s0, s56
	s_cselect_b32 s57, s17, s54
	s_cselect_b32 s56, s16, s51
	s_add_i32 s59, 0, 0x14000
	s_add_i32 m0, s26, 0xc000
	s_nop 0
	global_load_lds_dwordx4 v210, s[18:19]
	s_add_i32 m0, s26, 0xe000
	s_nop 0
	global_load_lds_dwordx4 v212, s[18:19]
	s_waitcnt vmcnt(8)
	s_waitcnt lgkmcnt(0)
	v_mfma_f32_16x16x32_bf16 v[186:189], v[66:69], v[150:153], 0
	v_mfma_f32_16x16x32_bf16 v[186:189], v[78:81], v[154:157], v[186:189]
	s_barrier
	s_setprio 1
	v_mfma_f32_16x16x32_bf16 v[182:185], v[98:101], v[154:157], 0
	v_mfma_f32_16x16x32_bf16 v[182:185], v[82:85], v[150:153], v[182:185]
	v_mfma_f32_16x16x32_bf16 v[134:137], v[82:85], v[158:161], 0
	v_mfma_f32_16x16x32_bf16 v[134:137], v[98:101], v[162:165], v[134:137]
	v_mfma_f32_16x16x32_bf16 v[138:141], v[78:81], v[162:165], 0
	v_mfma_f32_16x16x32_bf16 v[138:141], v[66:69], v[158:161], v[138:141]
	v_mfma_f32_16x16x32_bf16 v[114:117], v[66:69], v[170:173], 0
	v_mfma_f32_16x16x32_bf16 v[114:117], v[78:81], v[174:177], v[114:117]
	v_mfma_f32_16x16x32_bf16 v[110:113], v[98:101], v[174:177], 0
	v_mfma_f32_16x16x32_bf16 v[110:113], v[82:85], v[170:173], v[110:113]
	v_mfma_f32_16x16x32_bf16 v[86:89], v[82:85], v[178:181], 0
	v_mfma_f32_16x16x32_bf16 v[86:89], v[98:101], v[190:193], v[86:89]
	v_mfma_f32_16x16x32_bf16 v[90:93], v[78:81], v[190:193], 0
	v_mfma_f32_16x16x32_bf16 v[90:93], v[66:69], v[178:181], v[90:93]
	v_mfma_f32_16x16x32_bf16 v[166:169], v[106:109], v[150:153], 0
	v_mfma_f32_16x16x32_bf16 v[166:169], v[118:121], v[154:157], v[166:169]
	v_mfma_f32_16x16x32_bf16 v[146:149], v[142:145], v[154:157], 0
	v_mfma_f32_16x16x32_bf16 v[146:149], v[130:133], v[150:153], v[146:149]
	v_mfma_f32_16x16x32_bf16 v[122:125], v[130:133], v[158:161], 0
	v_mfma_f32_16x16x32_bf16 v[122:125], v[142:145], v[162:165], v[122:125]
	v_mfma_f32_16x16x32_bf16 v[126:129], v[118:121], v[162:165], 0
	v_mfma_f32_16x16x32_bf16 v[126:129], v[106:109], v[158:161], v[126:129]
	v_mfma_f32_16x16x32_bf16 v[102:105], v[106:109], v[170:173], 0
	v_mfma_f32_16x16x32_bf16 v[102:105], v[118:121], v[174:177], v[102:105]
	v_mfma_f32_16x16x32_bf16 v[94:97], v[142:145], v[174:177], 0
	v_mfma_f32_16x16x32_bf16 v[94:97], v[130:133], v[170:173], v[94:97]
	v_mfma_f32_16x16x32_bf16 v[70:73], v[130:133], v[178:181], 0
	v_mfma_f32_16x16x32_bf16 v[70:73], v[142:145], v[190:193], v[70:73]
	v_mfma_f32_16x16x32_bf16 v[74:77], v[118:121], v[190:193], 0
	v_mfma_f32_16x16x32_bf16 v[74:77], v[106:109], v[178:181], v[74:77]
	s_setprio 0
	s_barrier
	ds_read_b128 v[150:153], v234 offset:16384
	ds_read_b128 v[154:157], v234 offset:17408
	ds_read_b128 v[158:161], v234 offset:18432
	ds_read_b128 v[162:165], v234 offset:19456
	ds_read_b128 v[170:173], v234 offset:20480
	ds_read_b128 v[174:177], v234 offset:21504
	ds_read_b128 v[178:181], v234 offset:22528
	ds_read_b128 v[190:193], v234 offset:23552
	s_add_i32 s58, s58, s24
	v_lshl_add_u64 v[214:215], s[56:57], 0, v[194:195]
	s_mov_b32 m0, s58
	s_nop 0
	global_load_lds_dwordx4 v194, s[56:57]
	s_add_i32 m0, s58, 0x2000
	v_lshl_add_u64 v[216:217], s[56:57], 0, v[204:205]
	s_add_u32 s56, s56, s12
	s_addc_u32 s57, s57, 0
	s_add_i32 s58, s59, s24
	global_load_lds_dwordx4 v[216:217], off
	v_lshl_add_u64 v[218:219], s[56:57], 0, v[194:195]
	s_mov_b32 m0, s58
	v_lshl_add_u64 v[220:221], s[56:57], 0, v[204:205]
	global_load_lds_dwordx4 v194, s[56:57]
	s_add_i32 m0, s58, 0x2000
	s_nop 0
	global_load_lds_dwordx4 v204, s[56:57]
	s_waitcnt vmcnt(6)
	s_waitcnt lgkmcnt(0)
	v_mfma_f32_16x16x32_bf16 v[62:65], v[66:69], v[150:153], 0
	v_mfma_f32_16x16x32_bf16 v[62:65], v[78:81], v[154:157], v[62:65]
	s_barrier
	s_setprio 1
	v_mfma_f32_16x16x32_bf16 v[58:61], v[98:101], v[154:157], 0
	v_mfma_f32_16x16x32_bf16 v[58:61], v[82:85], v[150:153], v[58:61]
	v_mfma_f32_16x16x32_bf16 v[42:45], v[82:85], v[158:161], 0
	v_mfma_f32_16x16x32_bf16 v[42:45], v[98:101], v[162:165], v[42:45]
	v_mfma_f32_16x16x32_bf16 v[46:49], v[78:81], v[162:165], 0
	v_mfma_f32_16x16x32_bf16 v[46:49], v[66:69], v[158:161], v[46:49]
	v_mfma_f32_16x16x32_bf16 v[30:33], v[66:69], v[170:173], 0
	v_mfma_f32_16x16x32_bf16 v[30:33], v[78:81], v[174:177], v[30:33]
	v_mfma_f32_16x16x32_bf16 v[26:29], v[98:101], v[174:177], 0
	v_mfma_f32_16x16x32_bf16 v[26:29], v[82:85], v[170:173], v[26:29]
	v_mfma_f32_16x16x32_bf16 v[10:13], v[82:85], v[178:181], 0
	v_mfma_f32_16x16x32_bf16 v[10:13], v[98:101], v[190:193], v[10:13]
	v_mfma_f32_16x16x32_bf16 v[14:17], v[78:81], v[190:193], 0
	v_mfma_f32_16x16x32_bf16 v[14:17], v[66:69], v[178:181], v[14:17]
	v_mfma_f32_16x16x32_bf16 v[54:57], v[106:109], v[150:153], 0
	v_mfma_f32_16x16x32_bf16 v[54:57], v[118:121], v[154:157], v[54:57]
	v_mfma_f32_16x16x32_bf16 v[50:53], v[142:145], v[154:157], 0
	v_mfma_f32_16x16x32_bf16 v[50:53], v[130:133], v[150:153], v[50:53]
	v_mfma_f32_16x16x32_bf16 v[34:37], v[130:133], v[158:161], 0
	v_mfma_f32_16x16x32_bf16 v[34:37], v[142:145], v[162:165], v[34:37]
	v_mfma_f32_16x16x32_bf16 v[38:41], v[118:121], v[162:165], 0
	v_mfma_f32_16x16x32_bf16 v[38:41], v[106:109], v[158:161], v[38:41]
	v_mfma_f32_16x16x32_bf16 v[22:25], v[106:109], v[170:173], 0
	v_mfma_f32_16x16x32_bf16 v[22:25], v[118:121], v[174:177], v[22:25]
	v_mfma_f32_16x16x32_bf16 v[18:21], v[142:145], v[174:177], 0
	v_mfma_f32_16x16x32_bf16 v[18:21], v[130:133], v[170:173], v[18:21]
	v_mfma_f32_16x16x32_bf16 v[2:5], v[130:133], v[178:181], 0
	v_mfma_f32_16x16x32_bf16 v[2:5], v[142:145], v[190:193], v[2:5]
	v_mfma_f32_16x16x32_bf16 v[6:9], v[118:121], v[190:193], 0
	v_mfma_f32_16x16x32_bf16 v[6:9], v[106:109], v[178:181], v[6:9]
	s_setprio 0
	s_barrier
	s_mov_b32 m0, s26
	s_nop 0
	global_load_lds_dwordx4 v208, s[20:21]
	s_mov_b32 m0, s27
	s_nop 0
	global_load_lds_dwordx4 v206, s[20:21]
	ds_read_b128 v[66:69], v198 offset:32768
	ds_read_b128 v[78:81], v198 offset:33792
	ds_read_b128 v[82:85], v198 offset:34816
	ds_read_b128 v[98:101], v198 offset:35840
	ds_read_b128 v[106:109], v198 offset:49152
	ds_read_b128 v[118:121], v198 offset:50176
	ds_read_b128 v[130:133], v198 offset:51200
	ds_read_b128 v[142:145], v198 offset:52224
	ds_read_b128 v[150:153], v234 offset:32768
	ds_read_b128 v[154:157], v234 offset:33792
	ds_read_b128 v[158:161], v234 offset:34816
	ds_read_b128 v[162:165], v234 offset:35840
	ds_read_b128 v[170:173], v234 offset:36864
	ds_read_b128 v[174:177], v234 offset:37888
	ds_read_b128 v[178:181], v234 offset:38912
	ds_read_b128 v[190:193], v234 offset:39936
	s_add_i32 s56, 0, 0x18000
	s_add_i32 s57, 0, 0x1c000
	s_add_u32 s20, s20, s12
	s_addc_u32 s21, s21, 0
	s_mov_b32 m0, s28
	s_nop 0
	global_load_lds_dwordx4 v208, s[20:21]
	s_mov_b32 m0, s29
	s_nop 0
	global_load_lds_dwordx4 v206, s[20:21]
	s_waitcnt vmcnt(8)
	s_waitcnt lgkmcnt(0)
	v_mfma_f32_16x16x32_bf16 v[186:189], v[66:69], v[150:153], v[186:189]
	v_mfma_f32_16x16x32_bf16 v[186:189], v[78:81], v[154:157], v[186:189]
	s_barrier
	s_setprio 1
	v_mfma_f32_16x16x32_bf16 v[182:185], v[98:101], v[154:157], v[182:185]
	v_mfma_f32_16x16x32_bf16 v[182:185], v[82:85], v[150:153], v[182:185]
	v_mfma_f32_16x16x32_bf16 v[134:137], v[82:85], v[158:161], v[134:137]
	v_mfma_f32_16x16x32_bf16 v[134:137], v[98:101], v[162:165], v[134:137]
	v_mfma_f32_16x16x32_bf16 v[138:141], v[78:81], v[162:165], v[138:141]
	v_mfma_f32_16x16x32_bf16 v[138:141], v[66:69], v[158:161], v[138:141]
	v_mfma_f32_16x16x32_bf16 v[114:117], v[66:69], v[170:173], v[114:117]
	v_mfma_f32_16x16x32_bf16 v[114:117], v[78:81], v[174:177], v[114:117]
	v_mfma_f32_16x16x32_bf16 v[110:113], v[98:101], v[174:177], v[110:113]
	v_mfma_f32_16x16x32_bf16 v[110:113], v[82:85], v[170:173], v[110:113]
	v_mfma_f32_16x16x32_bf16 v[86:89], v[82:85], v[178:181], v[86:89]
	v_mfma_f32_16x16x32_bf16 v[86:89], v[98:101], v[190:193], v[86:89]
	v_mfma_f32_16x16x32_bf16 v[90:93], v[78:81], v[190:193], v[90:93]
	v_mfma_f32_16x16x32_bf16 v[90:93], v[66:69], v[178:181], v[90:93]
	v_mfma_f32_16x16x32_bf16 v[166:169], v[106:109], v[150:153], v[166:169]
	v_mfma_f32_16x16x32_bf16 v[166:169], v[118:121], v[154:157], v[166:169]
	v_mfma_f32_16x16x32_bf16 v[146:149], v[142:145], v[154:157], v[146:149]
	v_mfma_f32_16x16x32_bf16 v[146:149], v[130:133], v[150:153], v[146:149]
	v_mfma_f32_16x16x32_bf16 v[122:125], v[130:133], v[158:161], v[122:125]
	v_mfma_f32_16x16x32_bf16 v[122:125], v[142:145], v[162:165], v[122:125]
	v_mfma_f32_16x16x32_bf16 v[126:129], v[118:121], v[162:165], v[126:129]
	v_mfma_f32_16x16x32_bf16 v[126:129], v[106:109], v[158:161], v[126:129]
	v_mfma_f32_16x16x32_bf16 v[102:105], v[106:109], v[170:173], v[102:105]
	v_mfma_f32_16x16x32_bf16 v[102:105], v[118:121], v[174:177], v[102:105]
	v_mfma_f32_16x16x32_bf16 v[94:97], v[142:145], v[174:177], v[94:97]
	v_mfma_f32_16x16x32_bf16 v[94:97], v[130:133], v[170:173], v[94:97]
	v_mfma_f32_16x16x32_bf16 v[70:73], v[130:133], v[178:181], v[70:73]
	v_mfma_f32_16x16x32_bf16 v[70:73], v[142:145], v[190:193], v[70:73]
	v_mfma_f32_16x16x32_bf16 v[74:77], v[118:121], v[190:193], v[74:77]
	v_mfma_f32_16x16x32_bf16 v[74:77], v[106:109], v[178:181], v[74:77]
	s_setprio 0
	s_barrier
	ds_read_b128 v[150:153], v234 offset:49152
	ds_read_b128 v[154:157], v234 offset:50176
	ds_read_b128 v[158:161], v234 offset:51200
	ds_read_b128 v[162:165], v234 offset:52224
	ds_read_b128 v[170:173], v234 offset:53248
	ds_read_b128 v[174:177], v234 offset:54272
	ds_read_b128 v[178:181], v234 offset:55296
	ds_read_b128 v[190:193], v234 offset:56320
	s_add_i32 s20, s56, s24
	v_lshl_add_u64 v[214:215], v[214:215], 0, s[94:95]
	s_mov_b32 m0, s20
	s_nop 0
	global_load_lds_dwordx4 v[214:215], off
	v_lshl_add_u64 v[214:215], v[216:217], 0, s[94:95]
	s_add_i32 m0, s20, 0x2000
	s_add_i32 s20, s57, s24
	global_load_lds_dwordx4 v[214:215], off
	v_lshl_add_u64 v[214:215], v[218:219], 0, s[94:95]
	s_mov_b32 m0, s20
	s_nop 0
	global_load_lds_dwordx4 v[214:215], off
	v_lshl_add_u64 v[214:215], v[220:221], 0, s[94:95]
	s_add_i32 m0, s20, 0x2000
	s_nop 0
	global_load_lds_dwordx4 v[214:215], off
	s_waitcnt vmcnt(6)
	s_waitcnt lgkmcnt(0)
	v_mfma_f32_16x16x32_bf16 v[62:65], v[66:69], v[150:153], v[62:65]
	v_mfma_f32_16x16x32_bf16 v[62:65], v[78:81], v[154:157], v[62:65]
	s_barrier
	s_setprio 1
	v_mfma_f32_16x16x32_bf16 v[58:61], v[98:101], v[154:157], v[58:61]
	v_mfma_f32_16x16x32_bf16 v[58:61], v[82:85], v[150:153], v[58:61]
	v_mfma_f32_16x16x32_bf16 v[42:45], v[82:85], v[158:161], v[42:45]
	v_mfma_f32_16x16x32_bf16 v[42:45], v[98:101], v[162:165], v[42:45]
	v_mfma_f32_16x16x32_bf16 v[46:49], v[78:81], v[162:165], v[46:49]
	v_mfma_f32_16x16x32_bf16 v[46:49], v[66:69], v[158:161], v[46:49]
	v_mfma_f32_16x16x32_bf16 v[30:33], v[66:69], v[170:173], v[30:33]
	v_mfma_f32_16x16x32_bf16 v[30:33], v[78:81], v[174:177], v[30:33]
	v_mfma_f32_16x16x32_bf16 v[26:29], v[98:101], v[174:177], v[26:29]
	v_mfma_f32_16x16x32_bf16 v[26:29], v[82:85], v[170:173], v[26:29]
	v_mfma_f32_16x16x32_bf16 v[10:13], v[82:85], v[178:181], v[10:13]
	v_mfma_f32_16x16x32_bf16 v[10:13], v[98:101], v[190:193], v[10:13]
	s_add_u32 s18, s18, 0x100
	v_mfma_f32_16x16x32_bf16 v[14:17], v[78:81], v[190:193], v[14:17]
	v_mfma_f32_16x16x32_bf16 v[14:17], v[66:69], v[178:181], v[14:17]
	s_addc_u32 s19, s19, 0
	v_mfma_f32_16x16x32_bf16 v[54:57], v[106:109], v[150:153], v[54:57]
	v_mfma_f32_16x16x32_bf16 v[54:57], v[118:121], v[154:157], v[54:57]
	s_add_u32 s51, s51, 0x100
	v_mfma_f32_16x16x32_bf16 v[50:53], v[142:145], v[154:157], v[50:53]
	v_mfma_f32_16x16x32_bf16 v[50:53], v[130:133], v[150:153], v[50:53]
	s_addc_u32 s54, s54, 0
	v_mfma_f32_16x16x32_bf16 v[34:37], v[130:133], v[158:161], v[34:37]
	v_mfma_f32_16x16x32_bf16 v[34:37], v[142:145], v[162:165], v[34:37]
	s_cmp_ge_u32 s55, s53
	v_mfma_f32_16x16x32_bf16 v[38:41], v[118:121], v[162:165], v[38:41]
	v_mfma_f32_16x16x32_bf16 v[38:41], v[106:109], v[158:161], v[38:41]
	s_mov_b32 s20, s55
	v_mfma_f32_16x16x32_bf16 v[22:25], v[106:109], v[170:173], v[22:25]
	v_mfma_f32_16x16x32_bf16 v[22:25], v[118:121], v[174:177], v[22:25]
	v_mfma_f32_16x16x32_bf16 v[18:21], v[142:145], v[174:177], v[18:21]
	v_mfma_f32_16x16x32_bf16 v[18:21], v[130:133], v[170:173], v[18:21]
	v_mfma_f32_16x16x32_bf16 v[2:5], v[130:133], v[178:181], v[2:5]
	v_mfma_f32_16x16x32_bf16 v[2:5], v[142:145], v[190:193], v[2:5]
	v_mfma_f32_16x16x32_bf16 v[6:9], v[118:121], v[190:193], v[6:9]
	v_mfma_f32_16x16x32_bf16 v[6:9], v[106:109], v[178:181], v[6:9]
	s_setprio 0
	s_barrier
	s_cbranch_scc1 .Lpeel_exit_5

.Lpeel_exit_5:
.LBB0_853:
	v_lshl_or_b32 v66, s39, 8, v199
	v_lshl_add_u32 v214, s50, 8, v197
	v_ashrrev_i32_e32 v67, 31, v66
	v_lshlrev_b64 v[216:217], 1, v[66:67]
	v_ashrrev_i32_e32 v215, 31, v214
	v_lshl_add_u64 v[66:67], s[86:87], 0, v[216:217]
	v_lshlrev_b64 v[232:233], 12, v[214:215]
	v_lshl_add_u64 v[68:69], v[66:67], 0, v[232:233]
	global_load_dwordx4 v[190:193], v[68:69], off
	global_load_dwordx4 v[178:181], v[68:69], off offset:256
	v_or_b32_e32 v68, 16, v214
	v_ashrrev_i32_e32 v69, 31, v68
	v_lshlrev_b64 v[230:231], 12, v[68:69]
	v_lshl_add_u64 v[68:69], v[66:67], 0, v[230:231]
	global_load_dwordx4 v[174:177], v[68:69], off
	global_load_dwordx4 v[170:173], v[68:69], off offset:256
	v_or_b32_e32 v68, 32, v214
	v_ashrrev_i32_e32 v69, 31, v68
	v_lshlrev_b64 v[228:229], 12, v[68:69]
	v_lshl_add_u64 v[68:69], v[66:67], 0, v[228:229]
	global_load_dwordx4 v[162:165], v[68:69], off
	global_load_dwordx4 v[158:161], v[68:69], off offset:256
	v_or_b32_e32 v68, 48, v214
	v_ashrrev_i32_e32 v69, 31, v68
	v_lshlrev_b64 v[226:227], 12, v[68:69]
	v_lshl_add_u64 v[68:69], v[66:67], 0, v[226:227]
	global_load_dwordx4 v[154:157], v[68:69], off
	global_load_dwordx4 v[150:153], v[68:69], off offset:256
	s_mov_b64 s[18:19], 0x80000
	v_lshl_add_u64 v[224:225], v[232:233], 0, s[18:19]
	s_mov_b64 s[18:19], 0x90000
	v_lshl_add_u64 v[222:223], v[232:233], 0, s[18:19]
	s_mov_b64 s[18:19], 0xa0000
	v_lshl_add_u64 v[68:69], v[66:67], 0, v[224:225]
	v_lshl_add_u64 v[220:221], v[232:233], 0, s[18:19]
	s_mov_b64 s[18:19], 0xb0000
	global_load_dwordx4 v[142:145], v[68:69], off
	global_load_dwordx4 v[130:133], v[68:69], off offset:256
	v_lshl_add_u64 v[68:69], v[66:67], 0, v[222:223]
	v_lshl_add_u64 v[218:219], v[232:233], 0, s[18:19]
	v_lshl_add_u64 v[232:233], s[86:87], 0, v[232:233]
	global_load_dwordx4 v[118:121], v[68:69], off
	global_load_dwordx4 v[106:109], v[68:69], off offset:256
	v_lshl_add_u64 v[68:69], v[66:67], 0, v[220:221]
	v_lshl_add_u64 v[66:67], v[66:67], 0, v[218:219]
	v_lshl_add_u64 v[232:233], v[232:233], 0, v[216:217]
	global_load_dwordx4 v[98:101], v[68:69], off
	global_load_dwordx4 v[82:85], v[68:69], off offset:256
	global_load_dwordx4 v[78:81], v[66:67], off
	s_nop 0
	global_load_dwordx4 v[66:69], v[66:67], off offset:256
	s_and_b64 vcc, exec, s[14:15]
	s_cbranch_vccz .Lalign_l5
	s_barrier

.LBB0_972:
	s_ashr_i32 s29, s28, 31
	s_lshl_b64 s[10:11], s[28:29], 20
	s_add_u32 s36, s46, s10
	s_addc_u32 s37, s47, s11
	s_and_b64 s[4:5], s[4:5], exec
	s_cselect_b32 s13, s37, s7
	s_cselect_b32 s29, s36, s6
	s_add_u32 s33, s6, 0x100
	s_addc_u32 s38, s7, 0
	s_mov_b32 s39, -2
	s_add_u32 vcc_lo, s0, 0xffffc000
	s_addc_u32 vcc_hi, s1, -1
	s_mov_b32 m0, s59
	s_nop 0
	global_load_lds_dwordx4 v146, vcc
	s_mov_b32 m0, s60
	s_nop 0
	global_load_lds_dwordx4 v148, vcc
	ds_read_b128 v[130:133], v246
	ds_read_b128 v[134:137], v246 offset:1024
	ds_read_b128 v[150:153], v246 offset:2048
	ds_read_b128 v[154:157], v246 offset:3072
	ds_read_b128 v[158:161], v246 offset:16384
	ds_read_b128 v[162:165], v246 offset:17408
	ds_read_b128 v[166:169], v246 offset:18432
	ds_read_b128 v[170:173], v246 offset:19456
	ds_read_b128 v[174:177], v247
	ds_read_b128 v[178:181], v247 offset:1024
	ds_read_b128 v[182:185], v247 offset:2048
	ds_read_b128 v[186:189], v247 offset:3072
	ds_read_b128 v[190:193], v247 offset:4096
	ds_read_b128 v[204:207], v247 offset:5120
	ds_read_b128 v[208:211], v247 offset:6144
	ds_read_b128 v[212:215], v247 offset:7168
	s_add_u32 s4, s0, 0x100
	s_addc_u32 s5, s1, 0
	s_add_i32 s40, 0, 0x10000
	s_cmp_eq_u32 s39, 28
	s_cselect_b32 s11, s35, s5
	s_cselect_b32 s10, s34, s4
	s_cselect_b32 s7, s13, s38
	s_cselect_b32 s6, s29, s33
	s_add_i32 s41, 0, 0x14000
	s_add_i32 m0, s49, 0xc000
	s_nop 0
	global_load_lds_dwordx4 v146, s[0:1]
	s_add_i32 m0, s49, 0xe000
	s_nop 0
	global_load_lds_dwordx4 v148, s[0:1]
	s_waitcnt vmcnt(8)
	s_waitcnt lgkmcnt(0)
	v_mfma_f32_16x16x32_bf16 v[126:129], v[130:133], v[174:177], 0
	v_mfma_f32_16x16x32_bf16 v[126:129], v[134:137], v[178:181], v[126:129]
	s_barrier
	s_setprio 1
	v_mfma_f32_16x16x32_bf16 v[62:65], v[154:157], v[178:181], 0
	v_mfma_f32_16x16x32_bf16 v[62:65], v[150:153], v[174:177], v[62:65]
	v_mfma_f32_16x16x32_bf16 v[58:61], v[150:153], v[182:185], 0
	v_mfma_f32_16x16x32_bf16 v[58:61], v[154:157], v[186:189], v[58:61]
	v_mfma_f32_16x16x32_bf16 v[122:125], v[134:137], v[186:189], 0
	v_mfma_f32_16x16x32_bf16 v[122:125], v[130:133], v[182:185], v[122:125]
	v_mfma_f32_16x16x32_bf16 v[114:117], v[130:133], v[190:193], 0
	v_mfma_f32_16x16x32_bf16 v[114:117], v[134:137], v[204:207], v[114:117]
	v_mfma_f32_16x16x32_bf16 v[50:53], v[154:157], v[204:207], 0
	v_mfma_f32_16x16x32_bf16 v[50:53], v[150:153], v[190:193], v[50:53]
	v_mfma_f32_16x16x32_bf16 v[42:45], v[150:153], v[208:211], 0
	v_mfma_f32_16x16x32_bf16 v[42:45], v[154:157], v[212:215], v[42:45]
	v_mfma_f32_16x16x32_bf16 v[106:109], v[134:137], v[212:215], 0
	v_mfma_f32_16x16x32_bf16 v[106:109], v[130:133], v[208:211], v[106:109]
	v_mfma_f32_16x16x32_bf16 v[118:121], v[158:161], v[174:177], 0
	v_mfma_f32_16x16x32_bf16 v[118:121], v[162:165], v[178:181], v[118:121]
	v_mfma_f32_16x16x32_bf16 v[54:57], v[170:173], v[178:181], 0
	v_mfma_f32_16x16x32_bf16 v[54:57], v[166:169], v[174:177], v[54:57]
	v_mfma_f32_16x16x32_bf16 v[46:49], v[166:169], v[182:185], 0
	v_mfma_f32_16x16x32_bf16 v[46:49], v[170:173], v[186:189], v[46:49]
	v_mfma_f32_16x16x32_bf16 v[110:113], v[162:165], v[186:189], 0
	v_mfma_f32_16x16x32_bf16 v[110:113], v[158:161], v[182:185], v[110:113]
	v_mfma_f32_16x16x32_bf16 v[102:105], v[158:161], v[190:193], 0
	v_mfma_f32_16x16x32_bf16 v[102:105], v[162:165], v[204:207], v[102:105]
	v_mfma_f32_16x16x32_bf16 v[38:41], v[170:173], v[204:207], 0
	v_mfma_f32_16x16x32_bf16 v[38:41], v[166:169], v[190:193], v[38:41]
	v_mfma_f32_16x16x32_bf16 v[34:37], v[166:169], v[208:211], 0
	v_mfma_f32_16x16x32_bf16 v[34:37], v[170:173], v[212:215], v[34:37]
	v_mfma_f32_16x16x32_bf16 v[98:101], v[162:165], v[212:215], 0
	v_mfma_f32_16x16x32_bf16 v[98:101], v[158:161], v[208:211], v[98:101]
	s_setprio 0
	s_barrier
	ds_read_b128 v[174:177], v247 offset:16384
	ds_read_b128 v[178:181], v247 offset:17408
	ds_read_b128 v[182:185], v247 offset:18432
	ds_read_b128 v[186:189], v247 offset:19456
	ds_read_b128 v[190:193], v247 offset:20480
	ds_read_b128 v[204:207], v247 offset:21504
	ds_read_b128 v[208:211], v247 offset:22528
	ds_read_b128 v[212:215], v247 offset:23552
	s_add_i32 s0, s40, s48
	s_mov_b32 m0, s0
	s_nop 0
	global_load_lds_dwordx4 v140, s[6:7]
	s_add_i32 m0, s0, 0x2000
	s_add_u32 s0, s6, 0x80000
	s_addc_u32 s1, s7, 0
	s_add_i32 s40, s41, s48
	global_load_lds_dwordx4 v144, s[6:7]
	s_mov_b32 m0, s40
	s_nop 0
	global_load_lds_dwordx4 v140, s[0:1]
	s_add_i32 m0, s40, 0x2000
	s_nop 0
	global_load_lds_dwordx4 v144, s[0:1]
	s_waitcnt vmcnt(6)
	s_waitcnt lgkmcnt(0)
	v_mfma_f32_16x16x32_bf16 v[94:97], v[130:133], v[174:177], 0
	v_mfma_f32_16x16x32_bf16 v[94:97], v[134:137], v[178:181], v[94:97]
	s_barrier
	s_setprio 1
	v_mfma_f32_16x16x32_bf16 v[30:33], v[154:157], v[178:181], 0
	v_mfma_f32_16x16x32_bf16 v[30:33], v[150:153], v[174:177], v[30:33]
	v_mfma_f32_16x16x32_bf16 v[26:29], v[150:153], v[182:185], 0
	v_mfma_f32_16x16x32_bf16 v[26:29], v[154:157], v[186:189], v[26:29]
	v_mfma_f32_16x16x32_bf16 v[90:93], v[134:137], v[186:189], 0
	v_mfma_f32_16x16x32_bf16 v[90:93], v[130:133], v[182:185], v[90:93]
	v_mfma_f32_16x16x32_bf16 v[82:85], v[130:133], v[190:193], 0
	v_mfma_f32_16x16x32_bf16 v[82:85], v[134:137], v[204:207], v[82:85]
	v_mfma_f32_16x16x32_bf16 v[18:21], v[154:157], v[204:207], 0
	v_mfma_f32_16x16x32_bf16 v[18:21], v[150:153], v[190:193], v[18:21]
	v_mfma_f32_16x16x32_bf16 v[10:13], v[150:153], v[208:211], 0
	v_mfma_f32_16x16x32_bf16 v[10:13], v[154:157], v[212:215], v[10:13]
	v_mfma_f32_16x16x32_bf16 v[74:77], v[134:137], v[212:215], 0
	v_mfma_f32_16x16x32_bf16 v[74:77], v[130:133], v[208:211], v[74:77]
	v_mfma_f32_16x16x32_bf16 v[86:89], v[158:161], v[174:177], 0
	v_mfma_f32_16x16x32_bf16 v[86:89], v[162:165], v[178:181], v[86:89]
	v_mfma_f32_16x16x32_bf16 v[22:25], v[170:173], v[178:181], 0
	v_mfma_f32_16x16x32_bf16 v[22:25], v[166:169], v[174:177], v[22:25]
	v_mfma_f32_16x16x32_bf16 v[14:17], v[166:169], v[182:185], 0
	v_mfma_f32_16x16x32_bf16 v[14:17], v[170:173], v[186:189], v[14:17]
	v_mfma_f32_16x16x32_bf16 v[78:81], v[162:165], v[186:189], 0
	v_mfma_f32_16x16x32_bf16 v[78:81], v[158:161], v[182:185], v[78:81]
	v_mfma_f32_16x16x32_bf16 v[70:73], v[158:161], v[190:193], 0
	v_mfma_f32_16x16x32_bf16 v[70:73], v[162:165], v[204:207], v[70:73]
	v_mfma_f32_16x16x32_bf16 v[6:9], v[170:173], v[204:207], 0
	v_mfma_f32_16x16x32_bf16 v[6:9], v[166:169], v[190:193], v[6:9]
	v_mfma_f32_16x16x32_bf16 v[2:5], v[166:169], v[208:211], 0
	v_mfma_f32_16x16x32_bf16 v[2:5], v[170:173], v[212:215], v[2:5]
	v_mfma_f32_16x16x32_bf16 v[66:69], v[162:165], v[212:215], 0
	v_mfma_f32_16x16x32_bf16 v[66:69], v[158:161], v[208:211], v[66:69]
	s_setprio 0
	s_barrier
	s_mov_b32 m0, s49
	s_nop 0
	global_load_lds_dwordx4 v138, s[10:11]
	s_mov_b32 m0, s70
	s_nop 0
	global_load_lds_dwordx4 v142, s[10:11]
	ds_read_b128 v[130:133], v246 offset:32768
	ds_read_b128 v[134:137], v246 offset:33792
	ds_read_b128 v[150:153], v246 offset:34816
	ds_read_b128 v[154:157], v246 offset:35840
	ds_read_b128 v[158:161], v246 offset:49152
	ds_read_b128 v[162:165], v246 offset:50176
	ds_read_b128 v[166:169], v246 offset:51200
	ds_read_b128 v[170:173], v246 offset:52224
	ds_read_b128 v[174:177], v247 offset:32768
	ds_read_b128 v[178:181], v247 offset:33792
	ds_read_b128 v[182:185], v247 offset:34816
	ds_read_b128 v[186:189], v247 offset:35840
	ds_read_b128 v[190:193], v247 offset:36864
	ds_read_b128 v[204:207], v247 offset:37888
	ds_read_b128 v[208:211], v247 offset:38912
	ds_read_b128 v[212:215], v247 offset:39936
	s_add_i32 s40, 0, 0x18000
	s_add_i32 s41, 0, 0x1c000
	s_add_u32 s0, s10, 0x4000
	s_addc_u32 s1, s11, 0
	s_mov_b32 m0, s71
	s_nop 0
	global_load_lds_dwordx4 v138, s[0:1]
	s_mov_b32 m0, s73
	s_nop 0
	global_load_lds_dwordx4 v142, s[0:1]
	s_waitcnt vmcnt(8)
	s_waitcnt lgkmcnt(0)
	v_mfma_f32_16x16x32_bf16 v[126:129], v[130:133], v[174:177], v[126:129]
	v_mfma_f32_16x16x32_bf16 v[126:129], v[134:137], v[178:181], v[126:129]
	s_barrier
	s_setprio 1
	v_mfma_f32_16x16x32_bf16 v[62:65], v[154:157], v[178:181], v[62:65]
	v_mfma_f32_16x16x32_bf16 v[62:65], v[150:153], v[174:177], v[62:65]
	v_mfma_f32_16x16x32_bf16 v[58:61], v[150:153], v[182:185], v[58:61]
	v_mfma_f32_16x16x32_bf16 v[58:61], v[154:157], v[186:189], v[58:61]
	v_mfma_f32_16x16x32_bf16 v[122:125], v[134:137], v[186:189], v[122:125]
	v_mfma_f32_16x16x32_bf16 v[122:125], v[130:133], v[182:185], v[122:125]
	v_mfma_f32_16x16x32_bf16 v[114:117], v[130:133], v[190:193], v[114:117]
	v_mfma_f32_16x16x32_bf16 v[114:117], v[134:137], v[204:207], v[114:117]
	v_mfma_f32_16x16x32_bf16 v[50:53], v[154:157], v[204:207], v[50:53]
	v_mfma_f32_16x16x32_bf16 v[50:53], v[150:153], v[190:193], v[50:53]
	v_mfma_f32_16x16x32_bf16 v[42:45], v[150:153], v[208:211], v[42:45]
	v_mfma_f32_16x16x32_bf16 v[42:45], v[154:157], v[212:215], v[42:45]
	v_mfma_f32_16x16x32_bf16 v[106:109], v[134:137], v[212:215], v[106:109]
	v_mfma_f32_16x16x32_bf16 v[106:109], v[130:133], v[208:211], v[106:109]
	v_mfma_f32_16x16x32_bf16 v[118:121], v[158:161], v[174:177], v[118:121]
	v_mfma_f32_16x16x32_bf16 v[118:121], v[162:165], v[178:181], v[118:121]
	v_mfma_f32_16x16x32_bf16 v[54:57], v[170:173], v[178:181], v[54:57]
	v_mfma_f32_16x16x32_bf16 v[54:57], v[166:169], v[174:177], v[54:57]
	v_mfma_f32_16x16x32_bf16 v[46:49], v[166:169], v[182:185], v[46:49]
	v_mfma_f32_16x16x32_bf16 v[46:49], v[170:173], v[186:189], v[46:49]
	v_mfma_f32_16x16x32_bf16 v[110:113], v[162:165], v[186:189], v[110:113]
	v_mfma_f32_16x16x32_bf16 v[110:113], v[158:161], v[182:185], v[110:113]
	v_mfma_f32_16x16x32_bf16 v[102:105], v[158:161], v[190:193], v[102:105]
	v_mfma_f32_16x16x32_bf16 v[102:105], v[162:165], v[204:207], v[102:105]
	v_mfma_f32_16x16x32_bf16 v[38:41], v[170:173], v[204:207], v[38:41]
	v_mfma_f32_16x16x32_bf16 v[38:41], v[166:169], v[190:193], v[38:41]
	v_mfma_f32_16x16x32_bf16 v[34:37], v[166:169], v[208:211], v[34:37]
	v_mfma_f32_16x16x32_bf16 v[34:37], v[170:173], v[212:215], v[34:37]
	v_mfma_f32_16x16x32_bf16 v[98:101], v[162:165], v[212:215], v[98:101]
	v_mfma_f32_16x16x32_bf16 v[98:101], v[158:161], v[208:211], v[98:101]
	s_setprio 0
	s_barrier
	ds_read_b128 v[174:177], v247 offset:49152
	ds_read_b128 v[178:181], v247 offset:50176
	ds_read_b128 v[182:185], v247 offset:51200
	ds_read_b128 v[186:189], v247 offset:52224
	ds_read_b128 v[190:193], v247 offset:53248
	ds_read_b128 v[204:207], v247 offset:54272
	ds_read_b128 v[208:211], v247 offset:55296
	ds_read_b128 v[212:215], v247 offset:56320
	s_add_i32 s0, s40, s48
	s_add_u32 vcc_lo, s6, s94
	s_addc_u32 vcc_hi, s7, s95
	s_mov_b32 m0, s0
	s_nop 0
	global_load_lds_dwordx4 v140, vcc
	s_add_i32 m0, s0, 0x2000
	s_add_u32 s0, s6, 0x80080
	s_addc_u32 s1, s7, 0
	s_add_i32 s6, s41, s48
	global_load_lds_dwordx4 v144, vcc
	s_mov_b32 m0, s6
	s_nop 0
	global_load_lds_dwordx4 v140, s[0:1]
	s_add_i32 m0, s6, 0x2000
	s_nop 0
	global_load_lds_dwordx4 v144, s[0:1]
	s_waitcnt vmcnt(6)
	s_waitcnt lgkmcnt(0)
	v_mfma_f32_16x16x32_bf16 v[94:97], v[130:133], v[174:177], v[94:97]
	v_mfma_f32_16x16x32_bf16 v[94:97], v[134:137], v[178:181], v[94:97]
	s_barrier
	s_setprio 1
	v_mfma_f32_16x16x32_bf16 v[30:33], v[154:157], v[178:181], v[30:33]
	v_mfma_f32_16x16x32_bf16 v[30:33], v[150:153], v[174:177], v[30:33]
	v_mfma_f32_16x16x32_bf16 v[26:29], v[150:153], v[182:185], v[26:29]
	v_mfma_f32_16x16x32_bf16 v[26:29], v[154:157], v[186:189], v[26:29]
	v_mfma_f32_16x16x32_bf16 v[90:93], v[134:137], v[186:189], v[90:93]
	v_mfma_f32_16x16x32_bf16 v[90:93], v[130:133], v[182:185], v[90:93]
	v_mfma_f32_16x16x32_bf16 v[82:85], v[130:133], v[190:193], v[82:85]
	v_mfma_f32_16x16x32_bf16 v[82:85], v[134:137], v[204:207], v[82:85]
	v_mfma_f32_16x16x32_bf16 v[18:21], v[154:157], v[204:207], v[18:21]
	v_mfma_f32_16x16x32_bf16 v[18:21], v[150:153], v[190:193], v[18:21]
	v_mfma_f32_16x16x32_bf16 v[10:13], v[150:153], v[208:211], v[10:13]
	v_mfma_f32_16x16x32_bf16 v[10:13], v[154:157], v[212:215], v[10:13]
	s_add_i32 s39, s39, 2
	v_mfma_f32_16x16x32_bf16 v[74:77], v[134:137], v[212:215], v[74:77]
	v_mfma_f32_16x16x32_bf16 v[74:77], v[130:133], v[208:211], v[74:77]
	s_add_u32 s33, s33, 0x100
	v_mfma_f32_16x16x32_bf16 v[86:89], v[158:161], v[174:177], v[86:89]
	v_mfma_f32_16x16x32_bf16 v[86:89], v[162:165], v[178:181], v[86:89]
	s_addc_u32 s38, s38, 0
	v_mfma_f32_16x16x32_bf16 v[22:25], v[170:173], v[178:181], v[22:25]
	v_mfma_f32_16x16x32_bf16 v[22:25], v[166:169], v[174:177], v[22:25]
	s_cmp_gt_u32 s39, 29
	v_mfma_f32_16x16x32_bf16 v[14:17], v[166:169], v[182:185], v[14:17]
	v_mfma_f32_16x16x32_bf16 v[14:17], v[170:173], v[186:189], v[14:17]
	s_mov_b64 s[0:1], s[4:5]
	v_mfma_f32_16x16x32_bf16 v[78:81], v[162:165], v[186:189], v[78:81]
	v_mfma_f32_16x16x32_bf16 v[78:81], v[158:161], v[182:185], v[78:81]
	v_mfma_f32_16x16x32_bf16 v[70:73], v[158:161], v[190:193], v[70:73]
	v_mfma_f32_16x16x32_bf16 v[70:73], v[162:165], v[204:207], v[70:73]
	v_mfma_f32_16x16x32_bf16 v[6:9], v[170:173], v[204:207], v[6:9]
	v_mfma_f32_16x16x32_bf16 v[6:9], v[166:169], v[190:193], v[6:9]
	v_mfma_f32_16x16x32_bf16 v[2:5], v[166:169], v[208:211], v[2:5]
	v_mfma_f32_16x16x32_bf16 v[2:5], v[170:173], v[212:215], v[2:5]
	v_mfma_f32_16x16x32_bf16 v[66:69], v[162:165], v[212:215], v[66:69]
	v_mfma_f32_16x16x32_bf16 v[66:69], v[158:161], v[208:211], v[66:69]
	s_setprio 0
	s_barrier
	s_cbranch_scc1 .Lpeel_exit_7

.Lpeel_exit_7:
.LBB0_976:
	s_and_b64 vcc, exec, s[2:3]
	s_and_b32 s4, s9, 1
	s_cbranch_vccnz .LBB0_979
	v_mov_b32_e32 v131, v0
	s_mov_b32 s7, s28
	v_readfirstlane_b32 s5, v131
	v_and_b32_e32 v130, 63, v131
	s_ashr_i32 s1, s5, 8
	s_bfe_u32 s6, s5, 0x20006
	s_mov_b32 s5, s62
	v_cmp_gt_u32_e32 vcc, 32, v130
	v_mov_b32_e32 v132, 0x1600
	s_xor_b32 s0, s4, 1
	v_cndmask_b32_e64 v132, v132, 0, vcc
	v_and_b32_e32 v131, 31, v131
	v_lshl_add_u32 v132, s7, 7, v132
	s_lshl_b32 s7, s6, 5
	s_lshl_b32 s9, s1, 2
	v_or3_b32 v132, v132, s7, v131
	s_mul_i32 s7, s0, 0x3000
	s_or_b32 s9, s9, s6
	s_add_i32 s7, s7, 0
	s_mulk_i32 s9, 0x600
	v_ashrrev_i32_e32 v133, 31, v132
	s_add_i32 s7, s7, s9
	v_lshlrev_b64 v[132:133], 2, v[132:133]
	s_add_i32 m0, s7, 0x20000
	v_lshl_add_u64 v[134:135], s[14:15], 0, v[132:133]
	global_load_lds_dword v[134:135], off
	v_lshl_add_u64 v[134:135], s[18:19], 0, v[132:133]
	s_add_i32 m0, s7, 0x20100
	s_nop 0
	global_load_lds_dword v[134:135], off
	v_lshl_add_u64 v[134:135], s[20:21], 0, v[132:133]
	s_add_i32 m0, s7, 0x20200
	v_lshl_add_u64 v[132:133], s[16:17], 0, v[132:133]
	global_load_lds_dword v[134:135], off
	s_add_i32 m0, s7, 0x20300
	s_cmp_lg_u32 s6, 0
	global_load_lds_dword v[132:133], off
	s_cbranch_scc1 .LBB0_979
	s_mulk_i32 s5, 0xfc
	s_mul_i32 s6, s1, 0x7e
	s_add_i32 s5, s6, s5
	s_add_i32 s6, s5, -2
	s_ashr_i32 s7, s6, 31
	s_lshl_b64 s[6:7], s[6:7], 3
	s_add_u32 s6, s80, s6
	s_addc_u32 s7, s81, s7
	s_lshl_b32 s0, s0, 11
	s_add_i32 s0, s0, 0
	s_lshl_b32 s1, s1, 10
	s_add_i32 s0, s0, s1
	v_lshlrev_b32_e32 v194, 2, v130
	s_add_i32 m0, s0, 0x26000
	v_lshl_add_u64 v[130:131], s[6:7], 0, v[194:195]
	global_load_lds_dword v194, s[6:7]
	s_mov_b64 s[6:7], 0x100
	v_lshl_add_u64 v[132:133], v[130:131], 0, s[6:7]
	s_add_i32 m0, s0, 0x26100
	s_mov_b64 s[6:7], 0x200
	global_load_lds_dword v[132:133], off
	v_lshl_add_u64 v[132:133], v[130:131], 0, s[6:7]
	s_add_i32 m0, s0, 0x26200
	s_mov_b64 s[6:7], 0x300
	global_load_lds_dword v[132:133], off
	v_lshl_add_u64 v[130:131], v[130:131], 0, s[6:7]
	s_add_i32 m0, s0, 0x26300
	s_nop 0
	global_load_lds_dword v[130:131], off

.LBB0_1440:
	s_add_u32 s46, s20, 0x100
	s_waitcnt lgkmcnt(0)
	s_addc_u32 s47, s21, 0
	s_mov_b32 s48, -2
	s_add_u32 vcc_lo, s18, 0xffea0000
	s_addc_u32 vcc_hi, s19, -1
	s_mov_b32 m0, s38
	s_nop 0
	global_load_lds_dwordx4 v210, vcc
	s_mov_b32 m0, s40
	s_nop 0
	global_load_lds_dwordx4 v212, vcc
	ds_read_b128 v[66:69], v198
	ds_read_b128 v[78:81], v198 offset:1024
	ds_read_b128 v[86:89], v198 offset:2048
	ds_read_b128 v[98:101], v198 offset:3072
	ds_read_b128 v[106:109], v198 offset:16384
	ds_read_b128 v[118:121], v198 offset:17408
	ds_read_b128 v[130:133], v198 offset:18432
	ds_read_b128 v[142:145], v198 offset:19456
	ds_read_b128 v[150:153], v234
	ds_read_b128 v[154:157], v234 offset:1024
	ds_read_b128 v[158:161], v234 offset:2048
	ds_read_b128 v[162:165], v234 offset:3072
	ds_read_b128 v[170:173], v234 offset:4096
	ds_read_b128 v[174:177], v234 offset:5120
	ds_read_b128 v[178:181], v234 offset:6144
	ds_read_b128 v[190:193], v234 offset:7168
	s_add_u32 s20, s18, 0x100
	s_addc_u32 s21, s19, 0
	s_add_i32 s49, 0, 0x10000
	s_cmpk_eq_i32 s48, 0x54
	s_cselect_b32 s25, s1, s21
	s_cselect_b32 s24, s0, s20
	s_cselect_b32 s23, s17, s47
	s_cselect_b32 s22, s16, s46
	s_add_i32 s50, 0, 0x14000
	s_add_i32 m0, s28, 0xc000
	s_nop 0
	global_load_lds_dwordx4 v210, s[18:19]
	s_add_i32 m0, s28, 0xe000
	s_nop 0
	global_load_lds_dwordx4 v212, s[18:19]
	s_waitcnt vmcnt(8)
	s_waitcnt lgkmcnt(0)
	v_mfma_f32_16x16x32_bf16 v[186:189], v[66:69], v[150:153], 0
	v_mfma_f32_16x16x32_bf16 v[186:189], v[78:81], v[154:157], v[186:189]
	s_barrier
	s_setprio 1
	v_mfma_f32_16x16x32_bf16 v[182:185], v[98:101], v[154:157], 0
	v_mfma_f32_16x16x32_bf16 v[182:185], v[86:89], v[150:153], v[182:185]
	v_mfma_f32_16x16x32_bf16 v[134:137], v[86:89], v[158:161], 0
	v_mfma_f32_16x16x32_bf16 v[134:137], v[98:101], v[162:165], v[134:137]
	v_mfma_f32_16x16x32_bf16 v[138:141], v[78:81], v[162:165], 0
	v_mfma_f32_16x16x32_bf16 v[138:141], v[66:69], v[158:161], v[138:141]
	v_mfma_f32_16x16x32_bf16 v[114:117], v[66:69], v[170:173], 0
	v_mfma_f32_16x16x32_bf16 v[114:117], v[78:81], v[174:177], v[114:117]
	v_mfma_f32_16x16x32_bf16 v[110:113], v[98:101], v[174:177], 0
	v_mfma_f32_16x16x32_bf16 v[110:113], v[86:89], v[170:173], v[110:113]
	v_mfma_f32_16x16x32_bf16 v[82:85], v[86:89], v[178:181], 0
	v_mfma_f32_16x16x32_bf16 v[82:85], v[98:101], v[190:193], v[82:85]
	v_mfma_f32_16x16x32_bf16 v[90:93], v[78:81], v[190:193], 0
	v_mfma_f32_16x16x32_bf16 v[90:93], v[66:69], v[178:181], v[90:93]
	v_mfma_f32_16x16x32_bf16 v[166:169], v[106:109], v[150:153], 0
	v_mfma_f32_16x16x32_bf16 v[166:169], v[118:121], v[154:157], v[166:169]
	v_mfma_f32_16x16x32_bf16 v[146:149], v[142:145], v[154:157], 0
	v_mfma_f32_16x16x32_bf16 v[146:149], v[130:133], v[150:153], v[146:149]
	v_mfma_f32_16x16x32_bf16 v[122:125], v[130:133], v[158:161], 0
	v_mfma_f32_16x16x32_bf16 v[122:125], v[142:145], v[162:165], v[122:125]
	v_mfma_f32_16x16x32_bf16 v[126:129], v[118:121], v[162:165], 0
	v_mfma_f32_16x16x32_bf16 v[126:129], v[106:109], v[158:161], v[126:129]
	v_mfma_f32_16x16x32_bf16 v[102:105], v[106:109], v[170:173], 0
	v_mfma_f32_16x16x32_bf16 v[102:105], v[118:121], v[174:177], v[102:105]
	v_mfma_f32_16x16x32_bf16 v[94:97], v[142:145], v[174:177], 0
	v_mfma_f32_16x16x32_bf16 v[94:97], v[130:133], v[170:173], v[94:97]
	v_mfma_f32_16x16x32_bf16 v[70:73], v[130:133], v[178:181], 0
	v_mfma_f32_16x16x32_bf16 v[70:73], v[142:145], v[190:193], v[70:73]
	v_mfma_f32_16x16x32_bf16 v[74:77], v[118:121], v[190:193], 0
	v_mfma_f32_16x16x32_bf16 v[74:77], v[106:109], v[178:181], v[74:77]
	s_setprio 0
	s_barrier
	ds_read_b128 v[150:153], v234 offset:16384
	ds_read_b128 v[154:157], v234 offset:17408
	ds_read_b128 v[158:161], v234 offset:18432
	ds_read_b128 v[162:165], v234 offset:19456
	ds_read_b128 v[170:173], v234 offset:20480
	ds_read_b128 v[174:177], v234 offset:21504
	ds_read_b128 v[178:181], v234 offset:22528
	ds_read_b128 v[190:193], v234 offset:23552
	s_add_i32 s18, s49, s26
	s_mov_b32 m0, s18
	s_nop 0
	global_load_lds_dwordx4 v194, s[22:23]
	s_add_i32 m0, s18, 0x2000
	s_add_u32 s18, s22, 0x160000
	s_addc_u32 s19, s23, 0
	s_add_i32 s49, s50, s26
	global_load_lds_dwordx4 v204, s[22:23]
	s_mov_b32 m0, s49
	s_nop 0
	global_load_lds_dwordx4 v194, s[18:19]
	s_add_i32 m0, s49, 0x2000
	s_nop 0
	global_load_lds_dwordx4 v204, s[18:19]
	s_waitcnt vmcnt(6)
	s_waitcnt lgkmcnt(0)
	v_mfma_f32_16x16x32_bf16 v[62:65], v[66:69], v[150:153], 0
	v_mfma_f32_16x16x32_bf16 v[62:65], v[78:81], v[154:157], v[62:65]
	s_barrier
	s_setprio 1
	v_mfma_f32_16x16x32_bf16 v[58:61], v[98:101], v[154:157], 0
	v_mfma_f32_16x16x32_bf16 v[58:61], v[86:89], v[150:153], v[58:61]
	v_mfma_f32_16x16x32_bf16 v[42:45], v[86:89], v[158:161], 0
	v_mfma_f32_16x16x32_bf16 v[42:45], v[98:101], v[162:165], v[42:45]
	v_mfma_f32_16x16x32_bf16 v[46:49], v[78:81], v[162:165], 0
	v_mfma_f32_16x16x32_bf16 v[46:49], v[66:69], v[158:161], v[46:49]
	v_mfma_f32_16x16x32_bf16 v[30:33], v[66:69], v[170:173], 0
	v_mfma_f32_16x16x32_bf16 v[30:33], v[78:81], v[174:177], v[30:33]
	v_mfma_f32_16x16x32_bf16 v[26:29], v[98:101], v[174:177], 0
	v_mfma_f32_16x16x32_bf16 v[26:29], v[86:89], v[170:173], v[26:29]
	v_mfma_f32_16x16x32_bf16 v[10:13], v[86:89], v[178:181], 0
	v_mfma_f32_16x16x32_bf16 v[10:13], v[98:101], v[190:193], v[10:13]
	v_mfma_f32_16x16x32_bf16 v[14:17], v[78:81], v[190:193], 0
	v_mfma_f32_16x16x32_bf16 v[14:17], v[66:69], v[178:181], v[14:17]
	v_mfma_f32_16x16x32_bf16 v[54:57], v[106:109], v[150:153], 0
	v_mfma_f32_16x16x32_bf16 v[54:57], v[118:121], v[154:157], v[54:57]
	v_mfma_f32_16x16x32_bf16 v[50:53], v[142:145], v[154:157], 0
	v_mfma_f32_16x16x32_bf16 v[50:53], v[130:133], v[150:153], v[50:53]
	v_mfma_f32_16x16x32_bf16 v[34:37], v[130:133], v[158:161], 0
	v_mfma_f32_16x16x32_bf16 v[34:37], v[142:145], v[162:165], v[34:37]
	v_mfma_f32_16x16x32_bf16 v[38:41], v[118:121], v[162:165], 0
	v_mfma_f32_16x16x32_bf16 v[38:41], v[106:109], v[158:161], v[38:41]
	v_mfma_f32_16x16x32_bf16 v[22:25], v[106:109], v[170:173], 0
	v_mfma_f32_16x16x32_bf16 v[22:25], v[118:121], v[174:177], v[22:25]
	v_mfma_f32_16x16x32_bf16 v[18:21], v[142:145], v[174:177], 0
	v_mfma_f32_16x16x32_bf16 v[18:21], v[130:133], v[170:173], v[18:21]
	v_mfma_f32_16x16x32_bf16 v[2:5], v[130:133], v[178:181], 0
	v_mfma_f32_16x16x32_bf16 v[2:5], v[142:145], v[190:193], v[2:5]
	v_mfma_f32_16x16x32_bf16 v[6:9], v[118:121], v[190:193], 0
	v_mfma_f32_16x16x32_bf16 v[6:9], v[106:109], v[178:181], v[6:9]
	s_setprio 0
	s_barrier
	s_mov_b32 m0, s28
	s_nop 0
	global_load_lds_dwordx4 v208, s[24:25]
	s_mov_b32 m0, s29
	s_nop 0
	global_load_lds_dwordx4 v206, s[24:25]
	ds_read_b128 v[66:69], v198 offset:32768
	ds_read_b128 v[78:81], v198 offset:33792
	ds_read_b128 v[86:89], v198 offset:34816
	ds_read_b128 v[98:101], v198 offset:35840
	ds_read_b128 v[106:109], v198 offset:49152
	ds_read_b128 v[118:121], v198 offset:50176
	ds_read_b128 v[130:133], v198 offset:51200
	ds_read_b128 v[142:145], v198 offset:52224
	ds_read_b128 v[150:153], v234 offset:32768
	ds_read_b128 v[154:157], v234 offset:33792
	ds_read_b128 v[158:161], v234 offset:34816
	ds_read_b128 v[162:165], v234 offset:35840
	ds_read_b128 v[170:173], v234 offset:36864
	ds_read_b128 v[174:177], v234 offset:37888
	ds_read_b128 v[178:181], v234 offset:38912
	ds_read_b128 v[190:193], v234 offset:39936
	s_add_i32 s49, 0, 0x18000
	s_add_i32 s50, 0, 0x1c000
	s_add_u32 s18, s24, 0x160000
	s_addc_u32 s19, s25, 0
	s_mov_b32 m0, s33
	s_nop 0
	global_load_lds_dwordx4 v208, s[18:19]
	s_mov_b32 m0, s37
	s_nop 0
	global_load_lds_dwordx4 v206, s[18:19]
	s_waitcnt vmcnt(8)
	s_waitcnt lgkmcnt(0)
	v_mfma_f32_16x16x32_bf16 v[186:189], v[66:69], v[150:153], v[186:189]
	v_mfma_f32_16x16x32_bf16 v[186:189], v[78:81], v[154:157], v[186:189]
	s_barrier
	s_setprio 1
	v_mfma_f32_16x16x32_bf16 v[182:185], v[98:101], v[154:157], v[182:185]
	v_mfma_f32_16x16x32_bf16 v[182:185], v[86:89], v[150:153], v[182:185]
	v_mfma_f32_16x16x32_bf16 v[134:137], v[86:89], v[158:161], v[134:137]
	v_mfma_f32_16x16x32_bf16 v[134:137], v[98:101], v[162:165], v[134:137]
	v_mfma_f32_16x16x32_bf16 v[138:141], v[78:81], v[162:165], v[138:141]
	v_mfma_f32_16x16x32_bf16 v[138:141], v[66:69], v[158:161], v[138:141]
	v_mfma_f32_16x16x32_bf16 v[114:117], v[66:69], v[170:173], v[114:117]
	v_mfma_f32_16x16x32_bf16 v[114:117], v[78:81], v[174:177], v[114:117]
	v_mfma_f32_16x16x32_bf16 v[110:113], v[98:101], v[174:177], v[110:113]
	v_mfma_f32_16x16x32_bf16 v[110:113], v[86:89], v[170:173], v[110:113]
	v_mfma_f32_16x16x32_bf16 v[82:85], v[86:89], v[178:181], v[82:85]
	v_mfma_f32_16x16x32_bf16 v[82:85], v[98:101], v[190:193], v[82:85]
	v_mfma_f32_16x16x32_bf16 v[90:93], v[78:81], v[190:193], v[90:93]
	v_mfma_f32_16x16x32_bf16 v[90:93], v[66:69], v[178:181], v[90:93]
	v_mfma_f32_16x16x32_bf16 v[166:169], v[106:109], v[150:153], v[166:169]
	v_mfma_f32_16x16x32_bf16 v[166:169], v[118:121], v[154:157], v[166:169]
	v_mfma_f32_16x16x32_bf16 v[146:149], v[142:145], v[154:157], v[146:149]
	v_mfma_f32_16x16x32_bf16 v[146:149], v[130:133], v[150:153], v[146:149]
	v_mfma_f32_16x16x32_bf16 v[122:125], v[130:133], v[158:161], v[122:125]
	v_mfma_f32_16x16x32_bf16 v[122:125], v[142:145], v[162:165], v[122:125]
	v_mfma_f32_16x16x32_bf16 v[126:129], v[118:121], v[162:165], v[126:129]
	v_mfma_f32_16x16x32_bf16 v[126:129], v[106:109], v[158:161], v[126:129]
	v_mfma_f32_16x16x32_bf16 v[102:105], v[106:109], v[170:173], v[102:105]
	v_mfma_f32_16x16x32_bf16 v[102:105], v[118:121], v[174:177], v[102:105]
	v_mfma_f32_16x16x32_bf16 v[94:97], v[142:145], v[174:177], v[94:97]
	v_mfma_f32_16x16x32_bf16 v[94:97], v[130:133], v[170:173], v[94:97]
	v_mfma_f32_16x16x32_bf16 v[70:73], v[130:133], v[178:181], v[70:73]
	v_mfma_f32_16x16x32_bf16 v[70:73], v[142:145], v[190:193], v[70:73]
	v_mfma_f32_16x16x32_bf16 v[74:77], v[118:121], v[190:193], v[74:77]
	v_mfma_f32_16x16x32_bf16 v[74:77], v[106:109], v[178:181], v[74:77]
	s_setprio 0
	s_barrier
	ds_read_b128 v[150:153], v234 offset:49152
	ds_read_b128 v[154:157], v234 offset:50176
	ds_read_b128 v[158:161], v234 offset:51200
	ds_read_b128 v[162:165], v234 offset:52224
	ds_read_b128 v[170:173], v234 offset:53248
	ds_read_b128 v[174:177], v234 offset:54272
	ds_read_b128 v[178:181], v234 offset:55296
	ds_read_b128 v[190:193], v234 offset:56320
	s_add_i32 s18, s49, s26
	s_add_u32 vcc_lo, s22, s94
	s_addc_u32 vcc_hi, s23, s95
	s_mov_b32 m0, s18
	s_nop 0
	global_load_lds_dwordx4 v194, vcc
	s_add_i32 m0, s18, 0x2000
	s_add_u32 s18, s22, 0x160080
	s_addc_u32 s19, s23, 0
	s_add_i32 s22, s50, s26
	global_load_lds_dwordx4 v204, vcc
	s_mov_b32 m0, s22
	s_nop 0
	global_load_lds_dwordx4 v194, s[18:19]
	s_add_i32 m0, s22, 0x2000
	s_nop 0
	global_load_lds_dwordx4 v204, s[18:19]
	s_waitcnt vmcnt(6)
	s_waitcnt lgkmcnt(0)
	v_mfma_f32_16x16x32_bf16 v[62:65], v[66:69], v[150:153], v[62:65]
	v_mfma_f32_16x16x32_bf16 v[62:65], v[78:81], v[154:157], v[62:65]
	s_barrier
	s_setprio 1
	v_mfma_f32_16x16x32_bf16 v[58:61], v[98:101], v[154:157], v[58:61]
	v_mfma_f32_16x16x32_bf16 v[58:61], v[86:89], v[150:153], v[58:61]
	v_mfma_f32_16x16x32_bf16 v[42:45], v[86:89], v[158:161], v[42:45]
	v_mfma_f32_16x16x32_bf16 v[42:45], v[98:101], v[162:165], v[42:45]
	v_mfma_f32_16x16x32_bf16 v[46:49], v[78:81], v[162:165], v[46:49]
	v_mfma_f32_16x16x32_bf16 v[46:49], v[66:69], v[158:161], v[46:49]
	v_mfma_f32_16x16x32_bf16 v[30:33], v[66:69], v[170:173], v[30:33]
	v_mfma_f32_16x16x32_bf16 v[30:33], v[78:81], v[174:177], v[30:33]
	v_mfma_f32_16x16x32_bf16 v[26:29], v[98:101], v[174:177], v[26:29]
	v_mfma_f32_16x16x32_bf16 v[26:29], v[86:89], v[170:173], v[26:29]
	v_mfma_f32_16x16x32_bf16 v[10:13], v[86:89], v[178:181], v[10:13]
	v_mfma_f32_16x16x32_bf16 v[10:13], v[98:101], v[190:193], v[10:13]
	s_add_i32 s48, s48, 2
	v_mfma_f32_16x16x32_bf16 v[14:17], v[78:81], v[190:193], v[14:17]
	v_mfma_f32_16x16x32_bf16 v[14:17], v[66:69], v[178:181], v[14:17]
	s_add_u32 s46, s46, 0x100
	v_mfma_f32_16x16x32_bf16 v[54:57], v[106:109], v[150:153], v[54:57]
	v_mfma_f32_16x16x32_bf16 v[54:57], v[118:121], v[154:157], v[54:57]
	s_addc_u32 s47, s47, 0
	v_mfma_f32_16x16x32_bf16 v[50:53], v[142:145], v[154:157], v[50:53]
	v_mfma_f32_16x16x32_bf16 v[50:53], v[130:133], v[150:153], v[50:53]
	s_cmpk_gt_u32 s48, 0x55
	v_mfma_f32_16x16x32_bf16 v[34:37], v[130:133], v[158:161], v[34:37]
	v_mfma_f32_16x16x32_bf16 v[34:37], v[142:145], v[162:165], v[34:37]
	s_mov_b64 s[18:19], s[20:21]
	v_mfma_f32_16x16x32_bf16 v[38:41], v[118:121], v[162:165], v[38:41]
	v_mfma_f32_16x16x32_bf16 v[38:41], v[106:109], v[158:161], v[38:41]
	v_mfma_f32_16x16x32_bf16 v[22:25], v[106:109], v[170:173], v[22:25]
	v_mfma_f32_16x16x32_bf16 v[22:25], v[118:121], v[174:177], v[22:25]
	v_mfma_f32_16x16x32_bf16 v[18:21], v[142:145], v[174:177], v[18:21]
	v_mfma_f32_16x16x32_bf16 v[18:21], v[130:133], v[170:173], v[18:21]
	v_mfma_f32_16x16x32_bf16 v[2:5], v[130:133], v[178:181], v[2:5]
	v_mfma_f32_16x16x32_bf16 v[2:5], v[142:145], v[190:193], v[2:5]
	v_mfma_f32_16x16x32_bf16 v[6:9], v[118:121], v[190:193], v[6:9]
	v_mfma_f32_16x16x32_bf16 v[6:9], v[106:109], v[178:181], v[6:9]
	s_setprio 0
	s_barrier
	s_cbranch_scc1 .Lpeel_exit_8

.Lpeel_exit_8:
.LBB0_1444:
	v_lshl_or_b32 v66, s44, 8, v199
	v_lshl_add_u32 v214, s45, 8, v197
	v_ashrrev_i32_e32 v67, 31, v66
	v_lshlrev_b64 v[216:217], 1, v[66:67]
	v_ashrrev_i32_e32 v215, 31, v214
	v_lshl_add_u64 v[66:67], s[86:87], 0, v[216:217]
	v_lshlrev_b64 v[200:201], 12, v[214:215]
	v_lshl_add_u64 v[68:69], v[66:67], 0, v[200:201]
	global_load_dwordx4 v[190:193], v[68:69], off
	global_load_dwordx4 v[178:181], v[68:69], off offset:256
	v_or_b32_e32 v68, 16, v214
	v_ashrrev_i32_e32 v69, 31, v68
	v_lshlrev_b64 v[230:231], 12, v[68:69]
	v_lshl_add_u64 v[68:69], v[66:67], 0, v[230:231]
	global_load_dwordx4 v[174:177], v[68:69], off
	global_load_dwordx4 v[170:173], v[68:69], off offset:256
	v_or_b32_e32 v68, 32, v214
	v_ashrrev_i32_e32 v69, 31, v68
	v_lshlrev_b64 v[228:229], 12, v[68:69]
	v_lshl_add_u64 v[68:69], v[66:67], 0, v[228:229]
	global_load_dwordx4 v[162:165], v[68:69], off
	global_load_dwordx4 v[158:161], v[68:69], off offset:256
	v_or_b32_e32 v68, 48, v214
	v_ashrrev_i32_e32 v69, 31, v68
	v_lshlrev_b64 v[226:227], 12, v[68:69]
	s_mov_b64 s[18:19], 0x80000
	v_lshl_add_u64 v[68:69], v[66:67], 0, v[226:227]
	v_lshl_add_u64 v[224:225], v[200:201], 0, s[18:19]
	s_mov_b64 s[18:19], 0x90000
	global_load_dwordx4 v[154:157], v[68:69], off
	global_load_dwordx4 v[150:153], v[68:69], off offset:256
	v_lshl_add_u64 v[222:223], v[200:201], 0, s[18:19]
	s_mov_b64 s[18:19], 0xa0000
	v_lshl_add_u64 v[220:221], v[200:201], 0, s[18:19]
	s_mov_b64 s[18:19], 0xb0000
	v_lshl_add_u64 v[218:219], v[200:201], 0, s[18:19]
	v_lshl_add_u64 v[200:201], s[86:87], 0, v[200:201]
	v_lshl_add_u64 v[232:233], v[200:201], 0, v[216:217]
	v_lshl_add_u64 v[68:69], v[66:67], 0, v[224:225]
	global_load_dwordx4 v[142:145], v[68:69], off
	global_load_dwordx4 v[130:133], v[68:69], off offset:256
	v_lshl_add_u64 v[68:69], v[66:67], 0, v[222:223]
	global_load_dwordx4 v[118:121], v[68:69], off
	global_load_dwordx4 v[106:109], v[68:69], off offset:256
	v_lshl_add_u64 v[68:69], v[66:67], 0, v[220:221]
	v_lshl_add_u64 v[66:67], v[66:67], 0, v[218:219]
	global_load_dwordx4 v[98:101], v[68:69], off
	global_load_dwordx4 v[86:89], v[68:69], off offset:256
	global_load_dwordx4 v[78:81], v[66:67], off
	s_nop 0
	global_load_dwordx4 v[66:69], v[66:67], off offset:256
	s_and_b64 vcc, exec, s[14:15]
	s_cbranch_vccz .Lalign_l8
	s_barrier
